# v76 + attention K-tile LDS swizzle widened from 3 to 4 row bits in MLA and dilated attention (bank-conflict-free ds_read_b128 of K fragments)
# baseline (speedup 1.0000x reference)
; #define VMW() asm volatile("s_waitcnt vmcnt(0)" ::: "memory")
; #define SWRITE_HK(bf) do { *(bf16x8*)(K_lds + (bf) * SHM_K + kws) = S.st_k0; *(bf16x8*)(K_lds + (bf) * SHM_K + kws + 32 * 256) = S.st_k1; \
;                            if constexpr (PE) *(bf16x8*)(lds + OFF_KPE + (bf) * SHM_KPE + pws) = S.st_kp; } while (0)
; template <bool PE>
; __device__ __forceinline__ void swa_prime(const BlockRef& cur, const Prm& P, char* lds, Seam<PE>& S) {
;     int tid_ = threadIdx.x; asm volatile("" : "+v"(tid_));
;     const int tid = tid_, wid = __builtin_amdgcn_readfirstlane(tid >> 6), lane = tid & 63, r32 = lane & 31, hi = lane >> 5;
;     const int sr = tid >> 4, sc = (tid & 15) * 8, kws = KSWZ(sr, sc * 2); char* K_lds = lds + OFF_K;
;     const int pr = tid >> 3, pc = (tid & 7) * 8, pws = pr * KPE_ROW + (tid & 7) * 16;
;     const unsigned kvoff = (unsigned)(sr * P.kvs + sc) * 2u, kpoff = (unsigned)(pr * P.kpes + pc) * 2u, qoff = (unsigned)((wid * QBLK + r32) * P.qs + hi * 8) * 2u, qpoff = (unsigned)((wid * QBLK + r32) * P.qpes + hi * 8) * 2u;
;     const int kb0 = swa_jlo(cur.P0, P.W) * KVBLK;
; #pragma unroll
;     for (int d0 = 0; d0 < 8; ++d0) S.qr[d0] = LDG(cur.Q, qoff + d0 * 32);
;     if constexpr (PE) {
; #pragma unroll
;         for (int d0 = 0; d0 < 4; ++d0) *(bf16x8*)(lds + OFF_QPE + wid * 4096 + d0 * 1024 + lane * 16) = LDG(cur.Qpe, qpoff + d0 * 32);
;     }
;     SLOAD_H(cur, kb0); VMW(); SWRITE_HK(0);
;     __syncthreads();
.LBB0_361:
	s_or_b64 exec, exec, s[4:5]
	v_readlane_b32 s4, v255, 25
	s_add_u32 s58, s28, 0x36a00000
	v_readlane_b32 s5, v255, 26
	s_addc_u32 s59, s29, 0
	s_waitcnt lgkmcnt(0)
	s_barrier
	v_readlane_b32 s6, v255, 27
	v_readlane_b32 s7, v255, 28
	s_lshl_b32 s14, s3, 8
	v_writelane_b32 v255, s4, 25
	s_and_b32 s68, s14, 0x700
	s_ashr_i32 s0, s3, 3
	v_writelane_b32 v255, s5, 26
	v_writelane_b32 v255, s6, 27
	v_writelane_b32 v255, s7, 28
	s_ashr_i32 s4, s3, 7
	s_ashr_i32 s5, s4, 31
	s_lshl_b64 s[6:7], s[4:5], 12
	s_or_b32 s6, s6, s68
	s_mul_i32 s14, s7, 0x1800
	s_mul_hi_u32 s15, s6, 0x1800
	s_and_b32 s1, s0, 15
	s_add_i32 s15, s15, s14
	s_mul_i32 s14, s6, 0x1800
	s_add_u32 s20, s10, s14
	s_addc_u32 s21, s11, s15
	s_lshl_b32 s23, s1, 7
	s_lshl_b32 s24, s1, 8
	s_add_u32 s14, s20, s24
	s_addc_u32 s15, s21, 0
	s_add_u32 s1, s20, s23
	s_addc_u32 s20, s21, 0
	s_add_u32 s50, s1, 0x1000
	s_addc_u32 s51, s20, 0
	s_ashr_i32 s1, s0, 31
	s_lshl_b64 s[0:1], s[0:1], 20
	s_add_u32 s86, s12, s0
	s_addc_u32 s87, s13, s1
	s_add_u32 s88, s86, 0x4000000
	s_addc_u32 s89, s87, 0
	s_lshl_b64 s[0:1], s[4:5], 19
	s_add_u32 s90, s8, s0
	s_addc_u32 s91, s9, s1
	s_lshl_b64 s[0:1], s[6:7], 12
	s_add_u32 s0, s58, s0
	s_addc_u32 s1, s59, s1
	v_mov_b32_e32 v3, v0
	s_add_u32 s78, s0, s24
	s_addc_u32 s79, s1, 0
	v_readfirstlane_b32 s0, v3
	s_ashr_i32 s0, s0, 6
	v_and_b32_e32 v4, 31, v3
	v_lshl_or_b32 v4, s0, 5, v4
	s_movk_i32 s1, 0xc00
	v_mul_lo_u32 v4, v4, s1
	v_lshrrev_b32_e32 v5, 2, v3
	v_and_or_b32 v4, v5, 8, v4
	s_lshl_b32 s0, s0, 12
	v_lshlrev_b32_e32 v9, 4, v3
	v_lshlrev_b32_e32 v8, 1, v4
	s_add_i32 s0, s0, 0
	v_and_b32_e32 v4, 0x3f0, v9
	v_add_u32_e32 v4, s0, v4
	global_load_dwordx4 v[160:163], v8, s[14:15]
	global_load_dwordx4 v[156:159], v8, s[14:15] offset:32
	global_load_dwordx4 v[152:155], v8, s[14:15] offset:64
	global_load_dwordx4 v[148:151], v8, s[14:15] offset:96
	global_load_dwordx4 v[144:147], v8, s[14:15] offset:128
	global_load_dwordx4 v[140:143], v8, s[14:15] offset:160
	global_load_dwordx4 v[136:139], v8, s[14:15] offset:192
	global_load_dwordx4 v[132:135], v8, s[14:15] offset:224
	v_add_u32_e32 v10, 0x15000, v4
	global_load_dwordx4 v[4:7], v8, s[50:51]
	s_movk_i32 s0, 0xff00
	v_bitop3_b32 v200, v9, s0, v228 bitop3:0xe0
	global_load_dwordx4 v[100:103], v200, s[88:89]
	s_movk_i32 s0, 0x90
	v_and_b32_e32 v16, 0x70, v9
	v_and_b32_e32 v17, 0xffffff00, v9
	s_mov_b32 s1, 0
	s_xor_b32 s69, s68, 0xf00
	s_mov_b32 s4, s68
	s_mov_b32 s73, s68
	s_mov_b64 s[84:85], s[90:91]
	s_mov_b64 s[62:63], s[78:79]
	s_mov_b64 s[70:71], s[88:89]
	s_mov_b64 s[60:61], s[86:87]
	s_waitcnt vmcnt(1)
	ds_write_b128 v10, v[4:7]
	global_load_dwordx4 v[4:7], v8, s[50:51] offset:32
	s_waitcnt vmcnt(0)
	ds_write_b128 v10, v[4:7] offset:1024
	global_load_dwordx4 v[4:7], v8, s[50:51] offset:64
	s_waitcnt vmcnt(0)
	ds_write_b128 v10, v[4:7] offset:2048
	global_load_dwordx4 v[4:7], v8, s[50:51] offset:96
	s_waitcnt vmcnt(0)
	ds_write_b128 v10, v[4:7] offset:3072
	v_ashrrev_i32_e32 v4, 3, v3
	v_mul_lo_u32 v18, v4, s0
	v_and_b32_e32 v3, 0xf0, v3
	s_movk_i32 s0, 0xf0
	v_bitop3_b32 v3, v9, v3, s0 bitop3:0x6c
	v_lshl_add_u64 v[8:9], s[86:87], 0, v[200:201]
	v_lshl_or_b32 v12, v4, 7, v16
	v_add_co_u32_e32 v4, vcc, 0x4002000, v8
	v_add3_u32 v3, 0, v17, v3
	s_nop 0
	v_addc_co_u32_e32 v5, vcc, 0, v9, vcc
	v_add_co_u32_e32 v8, vcc, 0x2000, v8
	global_load_dwordx4 v[104:107], v[4:5], off
	s_nop 0
	global_load_dwordx4 v[4:7], v200, s[86:87]
	v_addc_co_u32_e32 v9, vcc, 0, v9, vcc
	global_load_dwordx4 v[8:11], v[8:9], off
	s_nop 0
	global_load_dwordx4 v[12:15], v12, s[90:91]
	s_waitcnt vmcnt(0)
	s_waitcnt vmcnt(2)
	ds_write_b128 v3, v[4:7] offset:32768
	s_waitcnt vmcnt(1)
	ds_write_b128 v3, v[8:11] offset:40960
	v_add3_u32 v3, s34, v18, v16
	s_waitcnt vmcnt(0)
	ds_write_b128 v3, v[12:15]
	s_waitcnt lgkmcnt(0)
	s_barrier
	s_branch .LBB0_364

; template <int KB, bool SK, bool PE>
; __device__ __forceinline__ void qkt(f32x16& p0, f32x16& p1, const char* lds, int r32, int hi, int wid, int lane, const bf16x8* qr, bool act) {
;     ...
;     p0 = f32x16{}; p1 = f32x16{};
;     const char* kb[4];
; #pragma unroll
;     for (int dd = 0; dd < 4; ++dd) kb[dd] = lds + OFF_K + KB * SHM_K + KSWZ(r32, (dd * 16 + hi * 8) * 2);
; #pragma unroll
;     for (int d0 = 0; d0 < 8; ++d0) { const char* a = kb[d0 & 3] + (d0 >> 2) * 128;
;         bf16x8 b0 = *reinterpret_cast<const bf16x8*>(a);
;         bf16x8 b1 = *reinterpret_cast<const bf16x8*>(a + 32 * 256);
;         p0 = __builtin_amdgcn_mfma_f32_32x32x16_bf16(b0, qr[d0], p0, 0, 0, 0);
;         p1 = __builtin_amdgcn_mfma_f32_32x32x16_bf16(b1, qr[d0], p1, 0, 0, 0); }
;     if constexpr (PE) {
;         const char* kp = lds + OFF_KPE + KB * SHM_KPE + r32 * KPE_ROW + hi * 16;
;         const char* qp = lds + OFF_QPE + wid * 4096 + lane * 16;
; #pragma unroll
;         for (int d0 = 0; d0 < 4; ++d0) {
;             bf16x8 b0 = *reinterpret_cast<const bf16x8*>(kp + d0 * 32);
;             bf16x8 b1 = *reinterpret_cast<const bf16x8*>(kp + d0 * 32 + 32 * KPE_ROW);
;             bf16x8 qf = *reinterpret_cast<const bf16x8*>(qp + d0 * 1024);
;             p0 = __builtin_amdgcn_mfma_f32_32x32x16_bf16(b0, qf, p0, 0, 0, 0);
;             p1 = __builtin_amdgcn_mfma_f32_32x32x16_bf16(b1, qf, p1, 0, 0, 0); }
;     }
; template <bool PE, bool SK, bool LSE, bool EARLY>
; __device__ __forceinline__ void swa_block(const BlockRef& cur, const BlockRef& nxt, const Prm& P, char* lds, Seam<PE>& S) {
;     ...
;     const int qlo = cur.P0 + wid * QBLK, qm = qlo + r32 - 4 * hi;
;     char* V_lds = lds + OFF_V; char* K_lds = lds + OFF_K;
;     float* ws = (float*)(lds + OFF_WS) + wid * 64; float* li_l = ws, * al_l = ws + 32;
;     float m_reg = -1e30f, l_reg = 0; f32x16 o[4] = {};
;     const int sr = tid >> 4, sc = (tid & 15) * 8, vst0 = v_st(sr, sc), vst1 = v_st(32 + sr, sc), kws = KSWZ(sr, sc * 2);
;     const int pr = tid >> 3, pc = (tid & 7) * 8, pws = pr * KPE_ROW + (tid & 7) * 16;
;     const unsigned kvoff = (unsigned)(sr * P.kvs + sc) * 2u, kpoff = (unsigned)(pr * P.kpes + pc) * 2u;
;     const int vb0 = (int)(uintptr_t)lds + v_rd_base(lane);
;     ...
;     f32x16 pA0, pA1, pB0, pB1; float mnA, mnB, alA, alB; bf16x8 pa0, pa1, pa2, pa3;
;     SWRITE_HV(0); SBAR();
.LBB0_366:
	v_mov_b32_e32 v59, v0
	s_nop 0
	v_readfirstlane_b32 s1, v59
	s_ashr_i32 s5, s1, 6
	v_bfe_u32 v3, v59, 5, 1
	v_and_b32_e32 v218, 31, v59
	s_lshl_b32 s20, s5, 5
	v_lshlrev_b32_e32 v57, 2, v3
	s_add_i32 s1, s20, s4
	v_sub_u32_e32 v4, v218, v57
	v_add_u32_e32 v217, s1, v4
	v_ashrrev_i32_e32 v4, 4, v59
	v_and_b32_e32 v7, 0xfffff0, v4
	v_lshlrev_b32_e32 v8, 1, v4
	v_and_or_b32 v7, v8, 8, v7
	v_lshrrev_b32_e32 v8, 1, v4
	v_and_b32_e32 v9, 3, v4
	v_and_or_b32 v8, v8, 4, v9
	v_add_u32_e32 v9, 32, v4
	v_and_b32_e32 v10, 0xfffff0, v9
	v_lshlrev_b32_e32 v9, 1, v9
	v_lshlrev_b32_e32 v5, 3, v59
	v_and_or_b32 v9, v9, 8, v10
	v_and_b32_e32 v6, 0x78, v5
	v_lshrrev_b32_e32 v7, 1, v7
	v_bfe_u32 v5, v5, 5, 2
	v_lshrrev_b32_e32 v9, 1, v9
	v_or_b32_e32 v7, v7, v5
	v_lshlrev_b32_e32 v60, 1, v6
	v_or_b32_e32 v5, v9, v5
	v_lshlrev_b32_e32 v7, 9, v7
	v_lshlrev_b32_e32 v8, 6, v8
	v_and_b32_e32 v6, 48, v60
	v_lshlrev_b32_e32 v5, 9, v5
	v_lshlrev_b32_e32 v62, 8, v4
	v_lshlrev_b32_e32 v4, 4, v59
	v_and_b32_e32 v58, 63, v59
	v_or3_b32 v7, v7, v8, v6
	v_or3_b32 v5, v5, v8, v6
	v_ashrrev_i32_e32 v61, 3, v59
	v_and_b32_e32 v56, 0x70, v4
	v_or_b32_e32 v200, v60, v62
	v_lshl_or_b32 v210, v61, 7, v56
	v_lshlrev_b32_e32 v63, 4, v58
	v_add_u32_e32 v223, 0, v7
	v_add_u32_e32 v224, 0, v5
	ds_write_b128 v223, v[100:103]
	ds_write_b128 v224, v[104:107]
	v_lshl_add_u64 v[4:5], s[88:89], 0, v[200:201]
	s_movk_i32 s6, 0x4000
	v_add_co_u32_e32 v6, vcc, s6, v4
	s_movk_i32 s7, 0x6000
	s_nop 0
	v_addc_co_u32_e32 v7, vcc, 0, v5, vcc
	v_add_co_u32_e32 v4, vcc, s7, v4
	v_mov_b32_e32 v211, v201
	s_nop 0
	v_addc_co_u32_e32 v5, vcc, 0, v5, vcc
	global_load_dwordx4 v[36:39], v[6:7], off
	global_load_dwordx4 v[40:43], v[4:5], off
	v_lshl_add_u64 v[4:5], s[86:87], 0, v[200:201]
	v_add_co_u32_e32 v6, vcc, s6, v4
	s_nop 1
	v_addc_co_u32_e32 v7, vcc, 0, v5, vcc
	v_add_co_u32_e32 v4, vcc, s7, v4
	s_nop 1
	v_addc_co_u32_e32 v5, vcc, 0, v5, vcc
	global_load_dwordx4 v[44:47], v[6:7], off
	global_load_dwordx4 v[48:51], v[4:5], off
	v_lshl_add_u64 v[4:5], s[90:91], 0, v[210:211]
	v_add_co_u32_e32 v4, vcc, s43, v4
	s_nop 1
	v_addc_co_u32_e32 v5, vcc, 0, v5, vcc
	global_load_dwordx4 v[52:55], v[4:5], off
	v_lshlrev_b32_e32 v3, 4, v3
	v_lshlrev_b32_e32 v68, 4, v218
	v_and_b32_e32 v68, 0x80, v68
	v_lshl_or_b32 v68, v218, 8, v68
	v_xad_u32 v4, v3, v56, 0
	v_add_u32_e32 v222, v4, v68
	ds_read_b128 v[4:7], v222 offset:32768
	v_or_b32_e32 v8, 32, v3
	v_xad_u32 v8, v8, v56, 0
	v_add_u32_e32 v221, v8, v68
	ds_read_b128 v[64:67], v221 offset:32768
	v_or_b32_e32 v69, 64, v3
	v_xad_u32 v69, v69, v56, 0
	v_add_u32_e32 v220, v69, v68
	s_waitcnt lgkmcnt(1)
	v_mfma_f32_32x32x16_bf16 v[20:35], v[4:7], v[160:163], 0
	ds_read_b128 v[4:7], v222 offset:40960
	v_or_b32_e32 v69, 0x60, v3
	v_xad_u32 v69, v69, v56, 0
	v_add_u32_e32 v219, v69, v68
	s_lshl_b32 s5, s5, 12
	s_add_i32 s5, s5, 0
	s_add_i32 s5, s5, 0x15000
	s_waitcnt lgkmcnt(1)
	v_mfma_f32_32x32x16_bf16 v[20:35], v[64:67], v[156:159], v[20:35]
	ds_read_b128 v[64:67], v221 offset:40960
	v_add_u32_e32 v215, s5, v63
	s_movk_i32 s6, 0x90
	s_sub_i32 s5, s1, 63
	s_cmpk_lt_u32 s5, 0xfa2
	ds_read_b128 v[68:71], v215
	s_waitcnt lgkmcnt(2)
	v_mfma_f32_32x32x16_bf16 v[4:19], v[4:7], v[160:163], 0
	s_waitcnt lgkmcnt(1)
	v_mfma_f32_32x32x16_bf16 v[4:19], v[64:67], v[156:159], v[4:19]
	ds_read_b128 v[64:67], v220 offset:32768
	s_waitcnt lgkmcnt(0)
	v_mfma_f32_32x32x16_bf16 v[20:35], v[64:67], v[152:155], v[20:35]
	ds_read_b128 v[64:67], v220 offset:40960
	s_waitcnt lgkmcnt(0)
	v_mfma_f32_32x32x16_bf16 v[4:19], v[64:67], v[152:155], v[4:19]
	ds_read_b128 v[64:67], v219 offset:32768
	s_waitcnt lgkmcnt(0)
	v_mfma_f32_32x32x16_bf16 v[20:35], v[64:67], v[148:151], v[20:35]
	ds_read_b128 v[64:67], v219 offset:40960
	s_waitcnt lgkmcnt(0)
	v_mfma_f32_32x32x16_bf16 v[4:19], v[64:67], v[148:151], v[4:19]
	v_xor_b32_e32 v222, 0x80, v222
	ds_read_b128 v[64:67], v222 offset:32768
	s_waitcnt lgkmcnt(0)
	v_mfma_f32_32x32x16_bf16 v[20:35], v[64:67], v[144:147], v[20:35]
	ds_read_b128 v[64:67], v222 offset:40960
	v_xor_b32_e32 v222, 0x80, v222
	s_waitcnt lgkmcnt(0)
	v_mfma_f32_32x32x16_bf16 v[4:19], v[64:67], v[144:147], v[4:19]
	v_xor_b32_e32 v221, 0x80, v221
	ds_read_b128 v[64:67], v221 offset:32768
	s_waitcnt lgkmcnt(0)
	v_mfma_f32_32x32x16_bf16 v[20:35], v[64:67], v[140:143], v[20:35]
	ds_read_b128 v[64:67], v221 offset:40960
	v_xor_b32_e32 v221, 0x80, v221
	s_waitcnt lgkmcnt(0)
	v_mfma_f32_32x32x16_bf16 v[4:19], v[64:67], v[140:143], v[4:19]
	v_xor_b32_e32 v220, 0x80, v220
	ds_read_b128 v[64:67], v220 offset:32768
	s_waitcnt lgkmcnt(0)
	v_mfma_f32_32x32x16_bf16 v[20:35], v[64:67], v[136:139], v[20:35]
	ds_read_b128 v[64:67], v220 offset:40960
	v_xor_b32_e32 v220, 0x80, v220
	s_waitcnt lgkmcnt(0)
	v_mfma_f32_32x32x16_bf16 v[4:19], v[64:67], v[136:139], v[4:19]
	v_xor_b32_e32 v219, 0x80, v219
	ds_read_b128 v[64:67], v219 offset:32768
	s_waitcnt lgkmcnt(0)
	v_mfma_f32_32x32x16_bf16 v[20:35], v[64:67], v[132:135], v[20:35]
	ds_read_b128 v[64:67], v219 offset:40960
	v_xor_b32_e32 v219, 0x80, v219
	s_waitcnt lgkmcnt(0)
	v_mfma_f32_32x32x16_bf16 v[4:19], v[64:67], v[132:135], v[4:19]
	v_mov_b32_e32 v64, s34
	v_mad_u32_u24 v64, v218, s6, v64
	v_add_u32_e32 v232, v64, v3
	ds_read_b128 v[64:67], v232
	s_waitcnt lgkmcnt(0)
	v_mfma_f32_32x32x16_bf16 v[20:35], v[64:67], v[68:71], v[20:35]
	ds_read_b128 v[64:67], v232 offset:4608
	s_waitcnt lgkmcnt(0)
	v_mfma_f32_32x32x16_bf16 v[4:19], v[64:67], v[68:71], v[4:19]
	ds_read_b128 v[64:67], v232 offset:32
	ds_read_b128 v[68:71], v215 offset:1024
	s_waitcnt lgkmcnt(0)
	v_mfma_f32_32x32x16_bf16 v[20:35], v[64:67], v[68:71], v[20:35]
	ds_read_b128 v[64:67], v232 offset:4640
	s_waitcnt lgkmcnt(0)
	v_mfma_f32_32x32x16_bf16 v[4:19], v[64:67], v[68:71], v[4:19]
	ds_read_b128 v[64:67], v232 offset:64
	ds_read_b128 v[68:71], v215 offset:2048
	s_waitcnt lgkmcnt(0)
	v_mfma_f32_32x32x16_bf16 v[20:35], v[64:67], v[68:71], v[20:35]
	ds_read_b128 v[64:67], v232 offset:4672
	s_waitcnt lgkmcnt(0)
	v_mfma_f32_32x32x16_bf16 v[4:19], v[64:67], v[68:71], v[4:19]
	ds_read_b128 v[64:67], v232 offset:96
	ds_read_b128 v[68:71], v215 offset:3072
	s_waitcnt lgkmcnt(0)
	v_mfma_f32_32x32x16_bf16 v[20:35], v[64:67], v[68:71], v[20:35]
	ds_read_b128 v[64:67], v232 offset:4704
	s_waitcnt lgkmcnt(0)
	v_mfma_f32_32x32x16_bf16 v[4:19], v[64:67], v[68:71], v[4:19]
	s_cbranch_scc1 .LBB0_368
; __device__ __forceinline__ void mask_tile(f32x16& p0, f32x16& p1, int dq, unsigned W) {
;     const float NEG = -__builtin_inff();
; #pragma unroll
;     for (int r = 0; r < 16; ++r) {
;         const int c = (r & 3) + 8 * (r >> 2);
;         if ((unsigned)(dq - c) >= W) p0[r] = NEG;
;         if ((unsigned)(dq - c - 32) >= W) p1[r] = NEG;
;     }
; }
	v_cmp_gt_u32_e32 vcc, s27, v217
	v_subrev_u32_e32 v64, 32, v217
	s_nop 5
	v_cndmask_b32_e32 v20, v2, v20, vcc
	v_cmp_gt_u32_e32 vcc, s27, v64
	v_add_u32_e32 v64, -1, v217
	s_nop 0
	v_cndmask_b32_e32 v4, v2, v4, vcc
	v_cmp_gt_u32_e32 vcc, s27, v64
	v_subrev_u32_e32 v64, 33, v217
	s_nop 0
	v_cndmask_b32_e32 v21, v2, v21, vcc
	v_cmp_gt_u32_e32 vcc, s27, v64
	v_add_u32_e32 v64, -2, v217
	s_nop 0
	v_cndmask_b32_e32 v5, v2, v5, vcc
	v_cmp_gt_u32_e32 vcc, s27, v64
	v_subrev_u32_e32 v64, 34, v217
	s_nop 0
	v_cndmask_b32_e32 v22, v2, v22, vcc
	v_cmp_gt_u32_e32 vcc, s27, v64
	v_add_u32_e32 v64, -3, v217
	s_nop 0
	v_cndmask_b32_e32 v6, v2, v6, vcc
	v_cmp_gt_u32_e32 vcc, s27, v64
	v_subrev_u32_e32 v64, 35, v217
	s_nop 0
	v_cndmask_b32_e32 v23, v2, v23, vcc
	v_cmp_gt_u32_e32 vcc, s27, v64
	v_add_u32_e32 v64, -8, v217
	s_nop 0
	v_cndmask_b32_e32 v7, v2, v7, vcc
	v_cmp_gt_u32_e32 vcc, s27, v64
	v_subrev_u32_e32 v64, 40, v217
	s_nop 0
	v_cndmask_b32_e32 v24, v2, v24, vcc
	v_cmp_gt_u32_e32 vcc, s27, v64
	v_add_u32_e32 v64, -9, v217
	s_nop 0
	v_cndmask_b32_e32 v8, v2, v8, vcc
	v_cmp_gt_u32_e32 vcc, s27, v64
	v_subrev_u32_e32 v64, 41, v217
	s_nop 0
	v_cndmask_b32_e32 v25, v2, v25, vcc
	v_cmp_gt_u32_e32 vcc, s27, v64
	v_add_u32_e32 v64, -10, v217
	s_nop 0
	v_cndmask_b32_e32 v9, v2, v9, vcc
	v_cmp_gt_u32_e32 vcc, s27, v64
	v_subrev_u32_e32 v64, 42, v217
	s_nop 0
	v_cndmask_b32_e32 v26, v2, v26, vcc
	v_cmp_gt_u32_e32 vcc, s27, v64
	v_add_u32_e32 v64, -11, v217
	s_nop 0
	v_cndmask_b32_e32 v10, v2, v10, vcc
	v_cmp_gt_u32_e32 vcc, s27, v64
	v_subrev_u32_e32 v64, 43, v217
	s_nop 0
	v_cndmask_b32_e32 v27, v2, v27, vcc
	v_cmp_gt_u32_e32 vcc, s27, v64
	v_add_u32_e32 v64, -16, v217
	s_nop 0
	v_cndmask_b32_e32 v11, v2, v11, vcc
	v_cmp_gt_u32_e32 vcc, s27, v64
	v_subrev_u32_e32 v64, 48, v217
	s_nop 0
	v_cndmask_b32_e32 v28, v2, v28, vcc
	v_cmp_gt_u32_e32 vcc, s27, v64
	v_subrev_u32_e32 v64, 17, v217
	s_nop 0
	v_cndmask_b32_e32 v12, v2, v12, vcc
	v_cmp_gt_u32_e32 vcc, s27, v64
	v_subrev_u32_e32 v64, 49, v217
	s_nop 0
	v_cndmask_b32_e32 v29, v2, v29, vcc
	v_cmp_gt_u32_e32 vcc, s27, v64
	v_subrev_u32_e32 v64, 18, v217
	s_nop 0
	v_cndmask_b32_e32 v13, v2, v13, vcc
	v_cmp_gt_u32_e32 vcc, s27, v64
	v_subrev_u32_e32 v64, 50, v217
	s_nop 0
	v_cndmask_b32_e32 v30, v2, v30, vcc
	v_cmp_gt_u32_e32 vcc, s27, v64
	v_subrev_u32_e32 v64, 19, v217
	s_nop 0
	v_cndmask_b32_e32 v14, v2, v14, vcc
	v_cmp_gt_u32_e32 vcc, s27, v64
	v_subrev_u32_e32 v64, 51, v217
	s_nop 0
	v_cndmask_b32_e32 v31, v2, v31, vcc
	v_cmp_gt_u32_e32 vcc, s27, v64
	v_subrev_u32_e32 v64, 24, v217
	s_nop 0
	v_cndmask_b32_e32 v15, v2, v15, vcc
	v_cmp_gt_u32_e32 vcc, s27, v64
	v_subrev_u32_e32 v64, 56, v217
	s_nop 0
	v_cndmask_b32_e32 v32, v2, v32, vcc
	v_cmp_gt_u32_e32 vcc, s27, v64
	v_subrev_u32_e32 v64, 25, v217
	s_nop 0
	v_cndmask_b32_e32 v16, v2, v16, vcc
	v_cmp_gt_u32_e32 vcc, s27, v64
	v_subrev_u32_e32 v64, 57, v217
	s_nop 0
	v_cndmask_b32_e32 v33, v2, v33, vcc
	v_cmp_gt_u32_e32 vcc, s27, v64
	v_subrev_u32_e32 v64, 26, v217
	s_nop 0
	v_cndmask_b32_e32 v17, v2, v17, vcc
	v_cmp_gt_u32_e32 vcc, s27, v64
	v_subrev_u32_e32 v64, 58, v217
	s_nop 0
	v_cndmask_b32_e32 v34, v2, v34, vcc
	v_cmp_gt_u32_e32 vcc, s27, v64
	v_subrev_u32_e32 v64, 27, v217
	s_nop 0
	v_cndmask_b32_e32 v18, v2, v18, vcc
	v_cmp_gt_u32_e32 vcc, s27, v64
	v_subrev_u32_e32 v64, 59, v217
	s_nop 0
	v_cndmask_b32_e32 v35, v2, v35, vcc
	v_cmp_gt_u32_e32 vcc, s27, v64
	s_nop 1
	v_cndmask_b32_e32 v19, v2, v19, vcc
; #define SBAR() __builtin_amdgcn_sched_barrier(0)
; #define VMW() asm volatile("s_waitcnt vmcnt(0)" ::: "memory")
; #define SWRITE_HV(bf) do { *(bf16x8*)(V_lds + (bf) * SHM_V + vst0) = S.st_v0; *(bf16x8*)(V_lds + (bf) * SHM_V + vst1) = S.st_v1; } while (0)
; #define SWRITE_H(bf) do { SWRITE_HV(bf); SWRITE_HK(bf); } while (0)
; #define ACT(t) (KBASE(t) <= qlo + QBLK - 1 && KBASE(t) + KVBLK - 1 >= qlo - W + 1)
; #define MASKT(P0_, P1_, t) do { const int kb_ = KBASE(t); if ((!SK || ACT(t)) && (kb_ + KVBLK - 1 > qlo || kb_ <= qlo + QBLK - 1 - W)) mask_tile(P0_, P1_, qm - kb_, (unsigned)W); } while (0)
; __device__ __forceinline__ void partialSM(f32x16& p0, f32x16& p1, float& m_reg, float& mn, float& alpha, const float scale) {
;     float pmax = p0[0]; for (int r = 1; r < 16; ++r) pmax = fmaxf(pmax, p0[r]); for (int r = 0; r < 16; ++r) pmax = fmaxf(pmax, p1[r]);
;     { auto rr = __builtin_amdgcn_permlane32_swap(__float_as_uint(pmax), __float_as_uint(pmax), false, false);
;       pmax = fmaxf(__uint_as_float(rr[0]), __uint_as_float(rr[1])); }
;     const float C2 = 1.4426950408889634f * scale;
;     if (__builtin_expect(__all((pmax - m_reg) * scale <= THR), 1)) { mn = m_reg; alpha = 1.f; }
;     else { mn = fmaxf(m_reg, pmax); alpha = __builtin_amdgcn_exp2f((m_reg - mn) * C2); m_reg = mn; }
;     const float mnL = -mn * C2;
;     for (int r = 0; r < 16; ++r) p0[r] = fmaf(p0[r], C2, mnL); for (int r = 0; r < 16; ++r) p1[r] = fmaf(p1[r], C2, mnL);
;     for (int r = 0; r < 16; ++r) p0[r] = __builtin_amdgcn_exp2f(p0[r]);
; }
; template <bool PE, bool SK, bool LSE, bool EARLY>
; __device__ __forceinline__ void swa_block(const BlockRef& cur, const BlockRef& nxt, const Prm& P, char* lds, Seam<PE>& S) {
;     ...
;     f32x16 pA0, pA1, pB0, pB1; float mnA, mnB, alA, alB; bf16x8 pa0, pa1, pa2, pa3;
;     SWRITE_HV(0); SBAR();
;     if (NT > 1) { SLOAD_H(cur, KBASE(1)); }
;     SBAR(); qkt<0, SK, PE>(pA0, pA1, lds, r32, hi, wid, lane, S.qr, ACT(0));
;     MASKT(pA0, pA1, 0); partialSM(pA0, pA1, m_reg, mnA, alA, P.scale);
;     if (NT > 1) { VMW(); SWRITE_H(1); }
;     __syncthreads();
.LBB0_368:
	s_add_i32 s5, s4, 0xff
	s_lshr_b32 s5, s5, 6
	s_add_i32 s5, s5, 1
	s_cmpk_lt_u32 s4, 0xf01
	v_and_b32_e32 v59, 0xf0, v59
	s_movk_i32 s4, 0x90
	s_cselect_b32 s21, s5, 64
	v_bitop3_b32 v59, v60, v62, v59 bitop3:0xde
	v_mad_u64_u32 v[212:213], s[4:5], v61, s4, v[56:57]
	v_lshlrev_b32_e32 v56, 3, v58
	v_and_b32_e32 v60, 0xc0, v63
	v_and_or_b32 v56, v56, 24, v60
	v_lshlrev_b32_e32 v60, 1, v58
	v_lshlrev_b32_e32 v58, 6, v58
	v_and_b32_e32 v60, 32, v60
	v_and_b32_e32 v58, 0x800, v58
	s_cmp_lg_u32 0, -1
	v_or3_b32 v56, v56, v60, v58
	s_cselect_b32 s4, 0, 0
	v_add_u32_e32 v213, s4, v56
	v_max_f32_e32 v56, v21, v21
	v_max_f32_e32 v58, v20, v20
	v_max_f32_e32 v56, v58, v56
	v_max3_f32 v56, v56, v22, v23
	v_max3_f32 v56, v56, v24, v25
	v_max3_f32 v56, v56, v26, v27
	v_max3_f32 v56, v56, v28, v29
	v_max3_f32 v56, v56, v30, v31
	v_max3_f32 v56, v56, v32, v33
	v_max3_f32 v56, v56, v34, v35
	v_max3_f32 v56, v56, v4, v5
	v_max3_f32 v56, v56, v6, v7
	v_max3_f32 v56, v56, v8, v9
	v_max3_f32 v56, v56, v10, v11
	v_max3_f32 v56, v56, v12, v13
	v_max3_f32 v56, v56, v14, v15
	v_max3_f32 v56, v56, v16, v17
	v_max3_f32 v56, v56, v18, v19
	v_mov_b32_e32 v58, v56
	s_nop 1
	v_permlane32_swap_b32_e32 v56, v58
	v_max_f32_e32 v58, v58, v58
	v_max_f32_e32 v56, v56, v56
	v_max_f32_e32 v56, v56, v58
	v_add_f32_e32 v58, 0x7149f2ca, v56
	v_mul_f32_e32 v58, 0x3d93cd3a, v58
	v_max_f32_e32 v56, 0xf149f2ca, v56
	v_cmp_ge_f32_e32 vcc, s35, v58
	v_sub_f32_e32 v58, 0xf149f2ca, v56
	s_add_i32 s23, s1, 0xfffff01f
	v_mul_f32_e32 v58, 0x3dd53b94, v58
	v_exp_f32_e32 v58, v58
	s_cmp_eq_u64 vcc, exec
	s_cselect_b64 vcc, -1, 0
	v_cndmask_b32_e32 v185, v56, v229, vcc
	v_mul_f32_e32 v56, 0xbdd53b94, v185
	v_cndmask_b32_e64 v184, v58, 1.0, vcc
	v_mov_b32_e32 v58, v56
	s_add_i32 s4, 0, 0x12c00
	v_mul_u32_u24_e32 v64, 0x90, v218
	v_fmamk_f32 v20, v20, 0x3dd53b94, v56
	v_fmamk_f32 v21, v21, 0x3dd53b94, v56
	v_fmamk_f32 v22, v22, 0x3dd53b94, v56
	v_fmamk_f32 v23, v23, 0x3dd53b94, v56
	v_fmamk_f32 v24, v24, 0x3dd53b94, v56
	v_fmamk_f32 v25, v25, 0x3dd53b94, v56
	v_fmamk_f32 v26, v26, 0x3dd53b94, v56
	v_fmamk_f32 v27, v27, 0x3dd53b94, v56
	v_fmamk_f32 v28, v28, 0x3dd53b94, v56
	v_fmamk_f32 v29, v29, 0x3dd53b94, v56
	v_fmamk_f32 v30, v30, 0x3dd53b94, v56
	v_fmamk_f32 v31, v31, 0x3dd53b94, v56
	v_fmamk_f32 v32, v32, 0x3dd53b94, v56
	v_fmamk_f32 v33, v33, 0x3dd53b94, v56
	v_fmamk_f32 v34, v34, 0x3dd53b94, v56
	v_fmac_f32_e32 v58, 0x3dd53b94, v35
	v_pk_fma_f32 v[182:183], v[4:5], s[46:47], v[56:57] op_sel_hi:[1,0,0]
	v_add_u32_e32 v216, 0, v59
	v_add_u32_e32 v4, s4, v212
	v_exp_f32_e32 v236, v20
	v_exp_f32_e32 v237, v21
	v_exp_f32_e32 v199, v22
	v_exp_f32_e32 v235, v23
	v_exp_f32_e32 v197, v24
	v_exp_f32_e32 v214, v25
	v_exp_f32_e32 v196, v26
	v_exp_f32_e32 v198, v27
	v_exp_f32_e32 v193, v28
	v_exp_f32_e32 v195, v29
	v_exp_f32_e32 v191, v30
	v_exp_f32_e32 v194, v31
	v_exp_f32_e32 v188, v32
	v_exp_f32_e32 v192, v33
	v_exp_f32_e32 v187, v34
	v_exp_f32_e32 v189, v58
	s_waitcnt vmcnt(0)
	s_waitcnt vmcnt(4)
	ds_write_b128 v223, v[36:39] offset:16384
	s_waitcnt vmcnt(3)
	ds_write_b128 v224, v[40:43] offset:16384
	s_waitcnt vmcnt(2)
	ds_write_b128 v216, v[44:47] offset:49152
	s_waitcnt vmcnt(1)
	ds_write_b128 v216, v[48:51] offset:57344
	s_waitcnt vmcnt(0)
	ds_write_b128 v4, v[52:55]
	v_add_u32_e32 v4, s4, v64
	s_add_i32 s4, s1, 0xffffff45
	v_add_u32_e32 v5, s4, v218
	v_mov_b32_e32 v52, v201
	v_mov_b32_e32 v53, v201
	v_pk_fma_f32 v[168:169], v[18:19], s[46:47], v[56:57] op_sel_hi:[1,0,0]
	v_pk_fma_f32 v[170:171], v[16:17], s[46:47], v[56:57] op_sel_hi:[1,0,0]
	v_pk_fma_f32 v[172:173], v[14:15], s[46:47], v[56:57] op_sel_hi:[1,0,0]
	v_pk_fma_f32 v[174:175], v[12:13], s[46:47], v[56:57] op_sel_hi:[1,0,0]
	v_pk_fma_f32 v[176:177], v[10:11], s[46:47], v[56:57] op_sel_hi:[1,0,0]
	v_pk_fma_f32 v[178:179], v[8:9], s[46:47], v[56:57] op_sel_hi:[1,0,0]
	v_pk_fma_f32 v[180:181], v[6:7], s[46:47], v[56:57] op_sel_hi:[1,0,0]
	v_sub_u32_e32 v234, v5, v57
	v_mov_b32_e32 v54, v201
	v_mov_b32_e32 v55, v201
	v_mov_b32_e32 v56, v201
	v_mov_b32_e32 v57, v201
	v_mov_b32_e32 v58, v201
	v_mov_b32_e32 v59, v201
	v_mov_b32_e32 v60, v201
	v_mov_b32_e32 v61, v201
	v_mov_b32_e32 v62, v201
	v_mov_b32_e32 v63, v201
	v_mov_b32_e32 v64, v201
	v_mov_b32_e32 v65, v201
	v_mov_b32_e32 v66, v201
	v_mov_b32_e32 v67, v201
	v_add_u32_e32 v233, v4, v3
	v_mov_b64_e32 v[36:37], v[52:53]
	v_mov_b64_e32 v[20:21], v[52:53]
	v_mov_b64_e32 v[4:5], v[52:53]
	v_mov_b32_e32 v186, 0
	s_movk_i32 s42, 0xbf
	s_mov_b32 s52, 2
	s_movk_i32 s24, 0x180
	v_mov_b64_e32 v[38:39], v[54:55]
	v_mov_b64_e32 v[40:41], v[56:57]
	v_mov_b64_e32 v[42:43], v[58:59]
	v_mov_b64_e32 v[44:45], v[60:61]
	v_mov_b64_e32 v[46:47], v[62:63]
	v_mov_b64_e32 v[48:49], v[64:65]
	v_mov_b64_e32 v[50:51], v[66:67]
	v_mov_b64_e32 v[22:23], v[54:55]
	v_mov_b64_e32 v[24:25], v[56:57]
	v_mov_b64_e32 v[26:27], v[58:59]
	v_mov_b64_e32 v[28:29], v[60:61]
	v_mov_b64_e32 v[30:31], v[62:63]
	v_mov_b64_e32 v[32:33], v[64:65]
	v_mov_b64_e32 v[34:35], v[66:67]
	v_mov_b64_e32 v[6:7], v[54:55]
	v_mov_b64_e32 v[8:9], v[56:57]
	v_mov_b64_e32 v[10:11], v[58:59]
	v_mov_b64_e32 v[12:13], v[60:61]
	v_mov_b64_e32 v[14:15], v[62:63]
	v_mov_b64_e32 v[16:17], v[64:65]
	v_mov_b64_e32 v[18:19], v[66:67]
	s_waitcnt lgkmcnt(0)
	s_barrier
	s_branch .LBB0_370

; #define PK4(P, B_, OUT) do { const u32x4 w = {cvtpk(P[B_+0], P[B_+1]), cvtpk(P[B_+2], P[B_+3]), cvtpk(P[B_+4], P[B_+5]), cvtpk(P[B_+6], P[B_+7])};     \
;         OUT = *reinterpret_cast<const bf16x8*>(&w); } while (0)
; __device__ __forceinline__ void finishSM(f32x16& p0, f32x16& p1, float alpha, float& l_reg, bf16x8& pa0, bf16x8& pa1, bf16x8& pa2, bf16x8& pa3) {
;     for (int r = 0; r < 16; ++r) p1[r] = __builtin_amdgcn_exp2f(p1[r]);
;     float ps = 0; for (int r = 0; r < 16; ++r) ps += p0[r]; for (int r = 0; r < 16; ++r) ps += p1[r];
;     { auto rr = __builtin_amdgcn_permlane32_swap(__float_as_uint(ps), __float_as_uint(ps), false, false);
;       ps = __uint_as_float(rr[0]) + __uint_as_float(rr[1]); }
;     l_reg = l_reg * alpha + ps;
;     ...
;     PK4(p0, 0, pa0); PK4(p0, 8, pa1); PK4(p1, 0, pa2); PK4(p1, 8, pa3);
;     ...
; }
; template <int KB, bool SK, bool PE>
; __device__ __forceinline__ void qkt(f32x16& p0, f32x16& p1, const char* lds, int r32, int hi, int wid, int lane, const bf16x8* qr, bool act) {
;     if (SK && !act) { const float NEG = -__builtin_inff();
; #pragma unroll
;         for (int r = 0; r < 16; ++r) { p0[r] = NEG; p1[r] = NEG; } return; }
;     p0 = f32x16{}; p1 = f32x16{};
;     const char* kb[4];
; #pragma unroll
;     for (int dd = 0; dd < 4; ++dd) kb[dd] = lds + OFF_K + KB * SHM_K + KSWZ(r32, (dd * 16 + hi * 8) * 2);
; #pragma unroll
;     for (int d0 = 0; d0 < 8; ++d0) { const char* a = kb[d0 & 3] + (d0 >> 2) * 128;
;         bf16x8 b0 = *reinterpret_cast<const bf16x8*>(a);
;         bf16x8 b1 = *reinterpret_cast<const bf16x8*>(a + 32 * 256);
;         p0 = __builtin_amdgcn_mfma_f32_32x32x16_bf16(b0, qr[d0], p0, 0, 0, 0);
;         p1 = __builtin_amdgcn_mfma_f32_32x32x16_bf16(b1, qr[d0], p1, 0, 0, 0); }
;     if constexpr (PE) {
;         const char* kp = lds + OFF_KPE + KB * SHM_KPE + r32 * KPE_ROW + hi * 16;
;         const char* qp = lds + OFF_QPE + wid * 4096 + lane * 16;
; #pragma unroll
;         for (int d0 = 0; d0 < 4; ++d0) {
;             bf16x8 b0 = *reinterpret_cast<const bf16x8*>(kp + d0 * 32);
;             bf16x8 b1 = *reinterpret_cast<const bf16x8*>(kp + d0 * 32 + 32 * KPE_ROW);
;             bf16x8 qf = *reinterpret_cast<const bf16x8*>(qp + d0 * 1024);
;             p0 = __builtin_amdgcn_mfma_f32_32x32x16_bf16(b0, qf, p0, 0, 0, 0);
;             p1 = __builtin_amdgcn_mfma_f32_32x32x16_bf16(b1, qf, p1, 0, 0, 0); }
;     }
.LBB0_370:
	ds_read_b128 v[68:71], v222 offset:49152
	ds_read_b128 v[72:75], v222 offset:57344
	ds_read_b128 v[100:103], v221 offset:49152
	ds_read_b128 v[104:107], v221 offset:57344
	v_exp_f32_e32 v116, v176
	v_exp_f32_e32 v117, v177
	s_waitcnt lgkmcnt(3)
	v_mfma_f32_32x32x16_bf16 v[84:99], v[68:71], v[160:163], 0
	v_exp_f32_e32 v118, v174
	v_exp_f32_e32 v119, v175
	v_exp_f32_e32 v120, v172
	v_exp_f32_e32 v121, v173
	v_exp_f32_e32 v122, v170
	v_exp_f32_e32 v123, v171
	v_exp_f32_e32 v124, v168
	s_waitcnt lgkmcnt(2)
	v_mfma_f32_32x32x16_bf16 v[68:83], v[72:75], v[160:163], 0
	v_exp_f32_e32 v125, v169
	s_add_i32 s4, s42, 0xffffff81
	s_sub_i32 s5, s42, 64
	s_waitcnt lgkmcnt(1)
	v_mfma_f32_32x32x16_bf16 v[84:99], v[100:103], v[156:159], v[84:99]
	s_waitcnt lgkmcnt(0)
	v_mfma_f32_32x32x16_bf16 v[68:83], v[104:107], v[156:159], v[68:83]
	ds_read_b128 v[100:103], v220 offset:49152
	ds_read_b128 v[104:107], v220 offset:57344
	s_waitcnt lgkmcnt(1)
	v_mfma_f32_32x32x16_bf16 v[84:99], v[100:103], v[152:155], v[84:99]
	s_waitcnt lgkmcnt(0)
	v_mfma_f32_32x32x16_bf16 v[68:83], v[104:107], v[152:155], v[68:83]
	ds_read_b128 v[100:103], v219 offset:49152
	ds_read_b128 v[104:107], v219 offset:57344
	s_waitcnt lgkmcnt(1)
	v_mfma_f32_32x32x16_bf16 v[84:99], v[100:103], v[148:151], v[84:99]
	s_waitcnt lgkmcnt(0)
	v_mfma_f32_32x32x16_bf16 v[68:83], v[104:107], v[148:151], v[68:83]
	v_xor_b32_e32 v222, 0x80, v222
	ds_read_b128 v[100:103], v222 offset:49152
	ds_read_b128 v[104:107], v222 offset:57344
	v_xor_b32_e32 v222, 0x80, v222
	s_waitcnt lgkmcnt(1)
	v_mfma_f32_32x32x16_bf16 v[84:99], v[100:103], v[144:147], v[84:99]
	s_waitcnt lgkmcnt(0)
	v_mfma_f32_32x32x16_bf16 v[68:83], v[104:107], v[144:147], v[68:83]
	v_xor_b32_e32 v221, 0x80, v221
	ds_read_b128 v[100:103], v221 offset:49152
	ds_read_b128 v[104:107], v221 offset:57344
	v_xor_b32_e32 v221, 0x80, v221
	s_waitcnt lgkmcnt(1)
	v_mfma_f32_32x32x16_bf16 v[84:99], v[100:103], v[140:143], v[84:99]
	s_waitcnt lgkmcnt(0)
	v_mfma_f32_32x32x16_bf16 v[68:83], v[104:107], v[140:143], v[68:83]
	v_xor_b32_e32 v220, 0x80, v220
	ds_read_b128 v[100:103], v220 offset:49152
	ds_read_b128 v[104:107], v220 offset:57344
	v_xor_b32_e32 v220, 0x80, v220
	s_waitcnt lgkmcnt(1)
	v_mfma_f32_32x32x16_bf16 v[84:99], v[100:103], v[136:139], v[84:99]
	s_waitcnt lgkmcnt(0)
	v_mfma_f32_32x32x16_bf16 v[68:83], v[104:107], v[136:139], v[68:83]
	v_xor_b32_e32 v219, 0x80, v219
	ds_read_b128 v[100:103], v219 offset:49152
	ds_read_b128 v[104:107], v219 offset:57344
	v_xor_b32_e32 v219, 0x80, v219
	s_waitcnt lgkmcnt(1)
	v_mfma_f32_32x32x16_bf16 v[84:99], v[100:103], v[132:135], v[84:99]
	s_waitcnt lgkmcnt(0)
	v_mfma_f32_32x32x16_bf16 v[68:83], v[104:107], v[132:135], v[68:83]
	ds_read_b128 v[100:103], v233 offset:4608
	ds_read_b128 v[104:107], v215
	ds_read_b128 v[108:111], v233
	ds_read_b128 v[112:115], v233 offset:32
	s_waitcnt lgkmcnt(1)
	v_mfma_f32_32x32x16_bf16 v[84:99], v[108:111], v[104:107], v[84:99]
	v_mfma_f32_32x32x16_bf16 v[68:83], v[100:103], v[104:107], v[68:83]
	ds_read_b128 v[100:103], v233 offset:4640
	ds_read_b128 v[104:107], v215 offset:1024
	s_waitcnt lgkmcnt(0)
	v_mfma_f32_32x32x16_bf16 v[84:99], v[112:115], v[104:107], v[84:99]
	v_exp_f32_e32 v112, v180
	v_exp_f32_e32 v113, v181
	v_exp_f32_e32 v114, v178
	v_exp_f32_e32 v115, v179
	v_mfma_f32_32x32x16_bf16 v[68:83], v[100:103], v[104:107], v[68:83]
	ds_read_b128 v[100:103], v233 offset:64
	ds_read_b128 v[104:107], v233 offset:4672
	ds_read_b128 v[108:111], v215 offset:2048
	s_waitcnt lgkmcnt(0)
	v_mfma_f32_32x32x16_bf16 v[84:99], v[100:103], v[108:111], v[84:99]
	v_mfma_f32_32x32x16_bf16 v[68:83], v[104:107], v[108:111], v[68:83]
	ds_read_b128 v[100:103], v233 offset:96
	ds_read_b128 v[104:107], v233 offset:4704
	ds_read_b128 v[108:111], v215 offset:3072
	s_waitcnt lgkmcnt(0)
	v_mfma_f32_32x32x16_bf16 v[84:99], v[100:103], v[108:111], v[84:99]
	v_add_f32_e32 v100, 0, v236
	v_add_f32_e32 v100, v237, v100
	v_add_f32_e32 v100, v199, v100
	v_add_f32_e32 v100, v235, v100
	v_add_f32_e32 v100, v197, v100
	v_add_f32_e32 v100, v214, v100
	v_add_f32_e32 v100, v196, v100
	v_add_f32_e32 v100, v198, v100
	v_add_f32_e32 v100, v193, v100
	v_add_f32_e32 v100, v195, v100
	v_add_f32_e32 v100, v191, v100
	v_add_f32_e32 v100, v194, v100
	v_mfma_f32_32x32x16_bf16 v[68:83], v[104:107], v[108:111], v[68:83]
	v_exp_f32_e32 v110, v182
	v_add_f32_e32 v100, v188, v100
	v_exp_f32_e32 v111, v183
	v_add_f32_e32 v100, v192, v100
	v_add_f32_e32 v100, v187, v100
	v_add_f32_e32 v100, v189, v100
	v_add_f32_e32 v100, v110, v100
	v_add_f32_e32 v100, v111, v100
	v_add_f32_e32 v100, v112, v100
	v_add_f32_e32 v100, v113, v100
	v_add_f32_e32 v100, v114, v100
	v_add_f32_e32 v100, v115, v100
	v_add_f32_e32 v100, v116, v100
	v_add_f32_e32 v100, v117, v100
	v_add_f32_e32 v100, v118, v100
	v_add_f32_e32 v100, v119, v100
	v_add_f32_e32 v100, v120, v100
	v_add_f32_e32 v100, v121, v100
	v_add_f32_e32 v100, v122, v100
	v_add_f32_e32 v100, v123, v100
	v_add_f32_e32 v100, v124, v100
	v_add_f32_e32 v104, v125, v100
	v_mov_b32_e32 v105, v104
	s_nop 1
	v_permlane32_swap_b32_e32 v104, v105
	v_cvt_pk_bf16_f32 v100, v236, v237
	v_cvt_pk_bf16_f32 v101, v199, v235
	v_cvt_pk_bf16_f32 v102, v197, v214
	v_cvt_pk_bf16_f32 v103, v196, v198
	v_cvt_pk_bf16_f32 v106, v193, v195
	v_cvt_pk_bf16_f32 v107, v191, v194
	v_cvt_pk_bf16_f32 v108, v188, v192
	v_cvt_pk_bf16_f32 v109, v187, v189
	v_cvt_pk_bf16_f32 v110, v110, v111
	v_cvt_pk_bf16_f32 v111, v112, v113
	v_cvt_pk_bf16_f32 v112, v114, v115
	v_cvt_pk_bf16_f32 v113, v116, v117
	v_cvt_pk_bf16_f32 v114, v118, v119
	v_cvt_pk_bf16_f32 v115, v120, v121
	v_cvt_pk_bf16_f32 v116, v122, v123
	v_cvt_pk_bf16_f32 v117, v124, v125
	s_sub_i32 s44, s42, 63
	s_lshl_b64 s[6:7], s[44:45], 8
	s_add_u32 s54, s86, s6
	s_addc_u32 s55, s87, s7
	s_add_u32 s6, s88, s6
	s_addc_u32 s7, s89, s7
	v_lshl_add_u64 v[118:119], s[6:7], 0, v[200:201]
	v_add_co_u32_e32 v120, vcc, s43, v118
	s_lshl_b64 s[6:7], s[44:45], 7
	s_nop 0
	v_addc_co_u32_e32 v121, vcc, 0, v119, vcc
	global_load_dwordx4 v[164:167], v[118:119], off
	global_load_dwordx4 v[168:171], v[120:121], off
	v_lshl_add_u64 v[118:119], s[54:55], 0, v[200:201]
	s_add_u32 s6, s90, s6
	v_add_co_u32_e32 v120, vcc, s43, v118
	s_addc_u32 s7, s91, s7
	s_nop 0
	v_addc_co_u32_e32 v121, vcc, 0, v119, vcc
	global_load_dwordx4 v[172:175], v[118:119], off
	global_load_dwordx4 v[176:179], v[120:121], off
	v_lshl_add_u64 v[118:119], s[6:7], 0, v[210:211]
	global_load_dwordx4 v[180:183], v[118:119], off
	ds_read_b64_tr_b16 v[118:119], v213 offset:0
	ds_read_b64_tr_b16 v[120:121], v213 offset:0x100
	ds_read_b64_tr_b16 v[122:123], v213 offset:0x1000
	ds_read_b64_tr_b16 v[124:125], v213 offset:0x1100
	ds_read_b64_tr_b16 v[126:127], v213 offset:0x2000
	ds_read_b64_tr_b16 v[128:129], v213 offset:0x2100
	ds_read_b64_tr_b16 v[188:189], v213 offset:0x3000
	ds_read_b64_tr_b16 v[190:191], v213 offset:0x3100
	s_waitcnt lgkmcnt(0)
; __device__ __forceinline__ void mask_tile(f32x16& p0, f32x16& p1, int dq, unsigned W) {
;     const float NEG = -__builtin_inff();
; #pragma unroll
;     for (int r = 0; r < 16; ++r) {
;         const int c = (r & 3) + 8 * (r >> 2);
;         if ((unsigned)(dq - c) >= W) p0[r] = NEG;
;         if ((unsigned)(dq - c - 32) >= W) p1[r] = NEG;
;     }
; }
; template <int VB, bool SK>
; __device__ __forceinline__ void pv_tile(f32x16* o, int vb0, bf16x8 pa0, bf16x8 pa1, bf16x8 pa2, bf16x8 pa3, bool act) {
;     ...
;     PV_D0(0); PV_D0(1); PV_D0(2); PV_D0(3);
	s_nop 0
	v_mfma_f32_32x32x16_bf16 v[52:67], v[118:121], v[100:103], v[52:67]
	ds_read_b64_tr_b16 v[118:119], v213 offset:0x200
	ds_read_b64_tr_b16 v[120:121], v213 offset:0x300
	v_mfma_f32_32x32x16_bf16 v[52:67], v[122:125], v[106:109], v[52:67]
	ds_read_b64_tr_b16 v[122:123], v213 offset:0x1200
	ds_read_b64_tr_b16 v[124:125], v213 offset:0x1300
	v_mfma_f32_32x32x16_bf16 v[52:67], v[126:129], v[110:113], v[52:67]
	ds_read_b64_tr_b16 v[126:127], v213 offset:0x2200
	ds_read_b64_tr_b16 v[128:129], v213 offset:0x2300
	v_mfma_f32_32x32x16_bf16 v[52:67], v[188:191], v[114:117], v[52:67]
	ds_read_b64_tr_b16 v[188:189], v213 offset:0x3200
	ds_read_b64_tr_b16 v[190:191], v213 offset:0x3300
	s_waitcnt lgkmcnt(0)
	v_mfma_f32_32x32x16_bf16 v[36:51], v[118:121], v[100:103], v[36:51]
	ds_read_b64_tr_b16 v[118:119], v213 offset:0x400
	ds_read_b64_tr_b16 v[120:121], v213 offset:0x500
	v_mfma_f32_32x32x16_bf16 v[36:51], v[122:125], v[106:109], v[36:51]
	ds_read_b64_tr_b16 v[122:123], v213 offset:0x1400
	ds_read_b64_tr_b16 v[124:125], v213 offset:0x1500
	v_mfma_f32_32x32x16_bf16 v[36:51], v[126:129], v[110:113], v[36:51]
	ds_read_b64_tr_b16 v[126:127], v213 offset:0x2400
	ds_read_b64_tr_b16 v[128:129], v213 offset:0x2500
	v_mfma_f32_32x32x16_bf16 v[36:51], v[188:191], v[114:117], v[36:51]
	ds_read_b64_tr_b16 v[188:189], v213 offset:0x3400
	ds_read_b64_tr_b16 v[190:191], v213 offset:0x3500
	s_waitcnt lgkmcnt(0)
	v_mfma_f32_32x32x16_bf16 v[20:35], v[118:121], v[100:103], v[20:35]
	ds_read_b64_tr_b16 v[118:119], v213 offset:0x600
	ds_read_b64_tr_b16 v[120:121], v213 offset:0x700
	v_mfma_f32_32x32x16_bf16 v[20:35], v[122:125], v[106:109], v[20:35]
	ds_read_b64_tr_b16 v[122:123], v213 offset:0x1600
	ds_read_b64_tr_b16 v[124:125], v213 offset:0x1700
	v_mfma_f32_32x32x16_bf16 v[20:35], v[126:129], v[110:113], v[20:35]
	ds_read_b64_tr_b16 v[126:127], v213 offset:0x2600
	ds_read_b64_tr_b16 v[128:129], v213 offset:0x2700
	v_mfma_f32_32x32x16_bf16 v[20:35], v[188:191], v[114:117], v[20:35]
	ds_read_b64_tr_b16 v[188:189], v213 offset:0x3600
	ds_read_b64_tr_b16 v[190:191], v213 offset:0x3700
	s_waitcnt lgkmcnt(0)
	v_mfma_f32_32x32x16_bf16 v[4:19], v[118:121], v[100:103], v[4:19]
	s_cmp_le_i32 s5, s1
	s_cselect_b64 s[6:7], -1, 0
	s_cmp_gt_i32 s4, s23
	s_cselect_b64 s[4:5], -1, 0
	s_and_b64 s[4:5], s[4:5], s[6:7]
	s_and_b64 vcc, exec, s[4:5]
	v_mfma_f32_32x32x16_bf16 v[4:19], v[122:125], v[106:109], v[4:19]
	v_mfma_f32_32x32x16_bf16 v[4:19], v[126:129], v[110:113], v[4:19]
	v_mfma_f32_32x32x16_bf16 v[4:19], v[188:191], v[114:117], v[4:19]
	s_cbranch_vccnz .LBB0_372
	v_add_u32_e32 v100, 0x7b, v234
	v_cmp_gt_u32_e32 vcc, s27, v100
	v_add_u32_e32 v100, 0x5b, v234
	s_nop 0
	v_cndmask_b32_e32 v84, v2, v84, vcc
	v_cmp_gt_u32_e32 vcc, s27, v100
	v_add_u32_e32 v100, 0x7a, v234
	s_nop 0
	v_cndmask_b32_e32 v68, v2, v68, vcc
	v_cmp_gt_u32_e32 vcc, s27, v100
	v_add_u32_e32 v100, 0x5a, v234
	s_nop 0
	v_cndmask_b32_e32 v85, v2, v85, vcc
	v_cmp_gt_u32_e32 vcc, s27, v100
	v_add_u32_e32 v100, 0x79, v234
	s_nop 0
	v_cndmask_b32_e32 v69, v2, v69, vcc
	v_cmp_gt_u32_e32 vcc, s27, v100
	v_add_u32_e32 v100, 0x59, v234
	s_nop 0
	v_cndmask_b32_e32 v86, v2, v86, vcc
	v_cmp_gt_u32_e32 vcc, s27, v100
	v_add_u32_e32 v100, 0x78, v234
	s_nop 0
	v_cndmask_b32_e32 v70, v2, v70, vcc
	v_cmp_gt_u32_e32 vcc, s27, v100
	v_add_u32_e32 v100, 0x58, v234
	s_nop 0
	v_cndmask_b32_e32 v87, v2, v87, vcc
	v_cmp_gt_u32_e32 vcc, s27, v100
	v_add_u32_e32 v100, 0x73, v234
	s_nop 0
	v_cndmask_b32_e32 v71, v2, v71, vcc
	v_cmp_gt_u32_e32 vcc, s27, v100
	v_add_u32_e32 v100, 0x53, v234
	s_nop 0
	v_cndmask_b32_e32 v88, v2, v88, vcc
	v_cmp_gt_u32_e32 vcc, s27, v100
	v_add_u32_e32 v100, 0x72, v234
	s_nop 0
	v_cndmask_b32_e32 v72, v2, v72, vcc
	v_cmp_gt_u32_e32 vcc, s27, v100
	v_add_u32_e32 v100, 0x52, v234
	s_nop 0
	v_cndmask_b32_e32 v89, v2, v89, vcc
	v_cmp_gt_u32_e32 vcc, s27, v100
	v_add_u32_e32 v100, 0x71, v234
	s_nop 0
	v_cndmask_b32_e32 v73, v2, v73, vcc
	v_cmp_gt_u32_e32 vcc, s27, v100
	v_add_u32_e32 v100, 0x51, v234
	s_nop 0
	v_cndmask_b32_e32 v90, v2, v90, vcc
	v_cmp_gt_u32_e32 vcc, s27, v100
	v_add_u32_e32 v100, 0x70, v234
	s_nop 0
	v_cndmask_b32_e32 v74, v2, v74, vcc
	v_cmp_gt_u32_e32 vcc, s27, v100
	v_add_u32_e32 v100, 0x50, v234
	s_nop 0
	v_cndmask_b32_e32 v91, v2, v91, vcc
	v_cmp_gt_u32_e32 vcc, s27, v100
	v_add_u32_e32 v100, 0x6b, v234
	s_nop 0
	v_cndmask_b32_e32 v75, v2, v75, vcc
	v_cmp_gt_u32_e32 vcc, s27, v100
	v_add_u32_e32 v100, 0x4b, v234
	s_nop 0
	v_cndmask_b32_e32 v92, v2, v92, vcc
	v_cmp_gt_u32_e32 vcc, s27, v100
	v_add_u32_e32 v100, 0x6a, v234
	s_nop 0
	v_cndmask_b32_e32 v76, v2, v76, vcc
	v_cmp_gt_u32_e32 vcc, s27, v100
	v_add_u32_e32 v100, 0x4a, v234
	s_nop 0
	v_cndmask_b32_e32 v93, v2, v93, vcc
	v_cmp_gt_u32_e32 vcc, s27, v100
	v_add_u32_e32 v100, 0x69, v234
	s_nop 0
	v_cndmask_b32_e32 v77, v2, v77, vcc
	v_cmp_gt_u32_e32 vcc, s27, v100
	v_add_u32_e32 v100, 0x49, v234
	s_nop 0
	v_cndmask_b32_e32 v94, v2, v94, vcc
	v_cmp_gt_u32_e32 vcc, s27, v100
	v_add_u32_e32 v100, 0x68, v234
	s_nop 0
	v_cndmask_b32_e32 v78, v2, v78, vcc
	v_cmp_gt_u32_e32 vcc, s27, v100
	v_add_u32_e32 v100, 0x48, v234
	s_nop 0
	v_cndmask_b32_e32 v95, v2, v95, vcc
	v_cmp_gt_u32_e32 vcc, s27, v100
	v_add_u32_e32 v100, 0x63, v234
	s_nop 0
	v_cndmask_b32_e32 v79, v2, v79, vcc
	v_cmp_gt_u32_e32 vcc, s27, v100
	v_add_u32_e32 v100, 0x43, v234
	s_nop 0
	v_cndmask_b32_e32 v96, v2, v96, vcc
	v_cmp_gt_u32_e32 vcc, s27, v100
	v_add_u32_e32 v100, 0x62, v234
	s_nop 0
	v_cndmask_b32_e32 v80, v2, v80, vcc
	v_cmp_gt_u32_e32 vcc, s27, v100
	v_add_u32_e32 v100, 0x42, v234
	s_nop 0
	v_cndmask_b32_e32 v97, v2, v97, vcc
	v_cmp_gt_u32_e32 vcc, s27, v100
	v_add_u32_e32 v100, 0x61, v234
	s_nop 0
	v_cndmask_b32_e32 v81, v2, v81, vcc
	v_cmp_gt_u32_e32 vcc, s27, v100
	v_add_u32_e32 v100, 0x41, v234
	s_nop 0
	v_cndmask_b32_e32 v98, v2, v98, vcc
	v_cmp_gt_u32_e32 vcc, s27, v100
	v_add_u32_e32 v100, 0x60, v234
	s_nop 0
	v_cndmask_b32_e32 v82, v2, v82, vcc
	v_cmp_gt_u32_e32 vcc, s27, v100
	v_add_u32_e32 v100, 64, v234
	s_nop 0
	v_cndmask_b32_e32 v99, v2, v99, vcc
	v_cmp_gt_u32_e32 vcc, s27, v100
	s_nop 1
	v_cndmask_b32_e32 v83, v2, v83, vcc

; __device__ __forceinline__ void partialSM(f32x16& p0, f32x16& p1, float& m_reg, float& mn, float& alpha, const float scale) {
;     ...
;     const float C2 = 1.4426950408889634f * scale;
;     if (__builtin_expect(__all((pmax - m_reg) * scale <= THR), 1)) { mn = m_reg; alpha = 1.f; }
;     else { mn = fmaxf(m_reg, pmax); alpha = __builtin_amdgcn_exp2f((m_reg - mn) * C2); m_reg = mn; }
;     const float mnL = -mn * C2;
;     for (int r = 0; r < 16; ++r) p0[r] = fmaf(p0[r], C2, mnL); for (int r = 0; r < 16; ++r) p1[r] = fmaf(p1[r], C2, mnL);
;     for (int r = 0; r < 16; ++r) p0[r] = __builtin_amdgcn_exp2f(p0[r]);
; }
.LBB0_374:
	v_cndmask_b32_e64 v236, v100, v185, s[4:5]
	v_mul_f32_e32 v184, 0xbdd53b94, v236
	v_fmamk_f32 v84, v84, 0x3dd53b94, v184
	v_fmamk_f32 v85, v85, 0x3dd53b94, v184
	v_fmamk_f32 v86, v86, 0x3dd53b94, v184
	v_fmamk_f32 v87, v87, 0x3dd53b94, v184
	v_fmamk_f32 v88, v88, 0x3dd53b94, v184
	v_fmamk_f32 v89, v89, 0x3dd53b94, v184
	v_fmamk_f32 v90, v90, 0x3dd53b94, v184
	v_fmamk_f32 v91, v91, 0x3dd53b94, v184
	v_fmamk_f32 v92, v92, 0x3dd53b94, v184
	v_fmamk_f32 v93, v93, 0x3dd53b94, v184
	v_fmamk_f32 v94, v94, 0x3dd53b94, v184
	v_fmamk_f32 v95, v95, 0x3dd53b94, v184
	v_fmamk_f32 v96, v96, 0x3dd53b94, v184
	v_fmamk_f32 v97, v97, 0x3dd53b94, v184
	v_fmamk_f32 v98, v98, 0x3dd53b94, v184
	v_fmamk_f32 v99, v99, 0x3dd53b94, v184
	v_fmamk_f32 v185, v68, 0x3dd53b94, v184
	v_fmamk_f32 v186, v69, 0x3dd53b94, v184
	v_fmamk_f32 v187, v70, 0x3dd53b94, v184
	v_fmamk_f32 v188, v71, 0x3dd53b94, v184
	v_fmamk_f32 v189, v72, 0x3dd53b94, v184
	v_fmamk_f32 v190, v73, 0x3dd53b94, v184
	v_fmamk_f32 v191, v74, 0x3dd53b94, v184
	v_fmamk_f32 v192, v75, 0x3dd53b94, v184
	v_fmamk_f32 v193, v76, 0x3dd53b94, v184
	v_fmamk_f32 v194, v77, 0x3dd53b94, v184
	v_fmamk_f32 v195, v78, 0x3dd53b94, v184
	v_fmamk_f32 v196, v79, 0x3dd53b94, v184
	v_fmamk_f32 v197, v80, 0x3dd53b94, v184
	v_fmamk_f32 v198, v81, 0x3dd53b94, v184
	v_fmamk_f32 v199, v82, 0x3dd53b94, v184
	v_fmac_f32_e32 v184, 0x3dd53b94, v83
	v_exp_f32_e32 v68, v84
	v_exp_f32_e32 v69, v85
	v_exp_f32_e32 v70, v86
	v_exp_f32_e32 v71, v87
	v_exp_f32_e32 v72, v88
	v_exp_f32_e32 v73, v89
	v_exp_f32_e32 v74, v90
	v_exp_f32_e32 v75, v91
	v_exp_f32_e32 v76, v92
	v_exp_f32_e32 v77, v93
	v_exp_f32_e32 v78, v94
	v_exp_f32_e32 v79, v95
	v_exp_f32_e32 v80, v96
	v_exp_f32_e32 v81, v97
	v_exp_f32_e32 v82, v98
	v_exp_f32_e32 v83, v99
	s_waitcnt lgkmcnt(0)
	s_barrier
; #define PK4(P, B_, OUT) do { const u32x4 w = {cvtpk(P[B_+0], P[B_+1]), cvtpk(P[B_+2], P[B_+3]), cvtpk(P[B_+4], P[B_+5]), cvtpk(P[B_+6], P[B_+7])};     \
;         OUT = *reinterpret_cast<const bf16x8*>(&w); } while (0)
; __device__ __forceinline__ void finishSM(f32x16& p0, f32x16& p1, float alpha, float& l_reg, bf16x8& pa0, bf16x8& pa1, bf16x8& pa2, bf16x8& pa3) {
;     for (int r = 0; r < 16; ++r) p1[r] = __builtin_amdgcn_exp2f(p1[r]);
;     float ps = 0; for (int r = 0; r < 16; ++r) ps += p0[r]; for (int r = 0; r < 16; ++r) ps += p1[r];
;     { auto rr = __builtin_amdgcn_permlane32_swap(__float_as_uint(ps), __float_as_uint(ps), false, false);
;       ps = __uint_as_float(rr[0]) + __uint_as_float(rr[1]); }
;     l_reg = l_reg * alpha + ps;
;     ...
;     PK4(p0, 0, pa0); PK4(p0, 8, pa1); PK4(p1, 0, pa2); PK4(p1, 8, pa3);
;     ...
; }
; template <int KB, bool SK, bool PE>
; __device__ __forceinline__ void qkt(f32x16& p0, f32x16& p1, const char* lds, int r32, int hi, int wid, int lane, const bf16x8* qr, bool act) {
;     if (SK && !act) { const float NEG = -__builtin_inff();
; #pragma unroll
;         for (int r = 0; r < 16; ++r) { p0[r] = NEG; p1[r] = NEG; } return; }
;     p0 = f32x16{}; p1 = f32x16{};
;     const char* kb[4];
; #pragma unroll
;     for (int dd = 0; dd < 4; ++dd) kb[dd] = lds + OFF_K + KB * SHM_K + KSWZ(r32, (dd * 16 + hi * 8) * 2);
; #pragma unroll
;     for (int d0 = 0; d0 < 8; ++d0) { const char* a = kb[d0 & 3] + (d0 >> 2) * 128;
;         bf16x8 b0 = *reinterpret_cast<const bf16x8*>(a);
;         bf16x8 b1 = *reinterpret_cast<const bf16x8*>(a + 32 * 256);
;         p0 = __builtin_amdgcn_mfma_f32_32x32x16_bf16(b0, qr[d0], p0, 0, 0, 0);
;         p1 = __builtin_amdgcn_mfma_f32_32x32x16_bf16(b1, qr[d0], p1, 0, 0, 0); }
;     if constexpr (PE) {
;         const char* kp = lds + OFF_KPE + KB * SHM_KPE + r32 * KPE_ROW + hi * 16;
;         const char* qp = lds + OFF_QPE + wid * 4096 + lane * 16;
; #pragma unroll
;         for (int d0 = 0; d0 < 4; ++d0) {
;             bf16x8 b0 = *reinterpret_cast<const bf16x8*>(kp + d0 * 32);
;             bf16x8 b1 = *reinterpret_cast<const bf16x8*>(kp + d0 * 32 + 32 * KPE_ROW);
;             bf16x8 qf = *reinterpret_cast<const bf16x8*>(qp + d0 * 1024);
;             p0 = __builtin_amdgcn_mfma_f32_32x32x16_bf16(b0, qf, p0, 0, 0, 0);
;             p1 = __builtin_amdgcn_mfma_f32_32x32x16_bf16(b1, qf, p1, 0, 0, 0); }
;     }
	ds_read_b128 v[84:87], v222 offset:32768
	ds_read_b128 v[88:91], v222 offset:40960
	s_waitcnt lgkmcnt(1)
	v_mfma_f32_32x32x16_bf16 v[116:131], v[84:87], v[160:163], 0
	s_waitcnt lgkmcnt(0)
	v_mfma_f32_32x32x16_bf16 v[100:115], v[88:91], v[160:163], 0
	ds_read_b128 v[84:87], v221 offset:32768
	ds_read_b128 v[88:91], v221 offset:40960
	s_waitcnt lgkmcnt(1)
	v_mfma_f32_32x32x16_bf16 v[116:131], v[84:87], v[156:159], v[116:131]
	s_waitcnt lgkmcnt(0)
	v_mfma_f32_32x32x16_bf16 v[100:115], v[88:91], v[156:159], v[100:115]
	ds_read_b128 v[84:87], v220 offset:32768
	ds_read_b128 v[88:91], v220 offset:40960
	s_waitcnt lgkmcnt(1)
	v_mfma_f32_32x32x16_bf16 v[116:131], v[84:87], v[152:155], v[116:131]
	s_waitcnt lgkmcnt(0)
	v_mfma_f32_32x32x16_bf16 v[100:115], v[88:91], v[152:155], v[100:115]
	ds_read_b128 v[84:87], v219 offset:32768
	ds_read_b128 v[88:91], v219 offset:40960
	s_waitcnt lgkmcnt(1)
	v_mfma_f32_32x32x16_bf16 v[116:131], v[84:87], v[148:151], v[116:131]
	s_waitcnt lgkmcnt(0)
	v_mfma_f32_32x32x16_bf16 v[100:115], v[88:91], v[148:151], v[100:115]
	v_xor_b32_e32 v222, 0x80, v222
	ds_read_b128 v[84:87], v222 offset:32768
	ds_read_b128 v[88:91], v222 offset:40960
	v_xor_b32_e32 v222, 0x80, v222
	s_waitcnt lgkmcnt(1)
	v_mfma_f32_32x32x16_bf16 v[116:131], v[84:87], v[144:147], v[116:131]
	s_waitcnt lgkmcnt(0)
	v_mfma_f32_32x32x16_bf16 v[100:115], v[88:91], v[144:147], v[100:115]
	v_xor_b32_e32 v221, 0x80, v221
	ds_read_b128 v[84:87], v221 offset:32768
	ds_read_b128 v[88:91], v221 offset:40960
	v_xor_b32_e32 v221, 0x80, v221
	s_waitcnt lgkmcnt(1)
	v_mfma_f32_32x32x16_bf16 v[116:131], v[84:87], v[140:143], v[116:131]
	s_waitcnt lgkmcnt(0)
	v_mfma_f32_32x32x16_bf16 v[100:115], v[88:91], v[140:143], v[100:115]
	v_xor_b32_e32 v220, 0x80, v220
	ds_read_b128 v[84:87], v220 offset:32768
	ds_read_b128 v[88:91], v220 offset:40960
	v_xor_b32_e32 v220, 0x80, v220
	s_waitcnt lgkmcnt(1)
	v_mfma_f32_32x32x16_bf16 v[116:131], v[84:87], v[136:139], v[116:131]
	s_waitcnt lgkmcnt(0)
	v_mfma_f32_32x32x16_bf16 v[100:115], v[88:91], v[136:139], v[100:115]
	v_xor_b32_e32 v219, 0x80, v219
	ds_read_b128 v[84:87], v219 offset:32768
	ds_read_b128 v[88:91], v219 offset:40960
	v_xor_b32_e32 v219, 0x80, v219
	s_waitcnt lgkmcnt(1)
	v_mfma_f32_32x32x16_bf16 v[116:131], v[84:87], v[132:135], v[116:131]
	s_waitcnt lgkmcnt(0)
	v_mfma_f32_32x32x16_bf16 v[100:115], v[88:91], v[132:135], v[100:115]
	ds_read_b128 v[84:87], v232 offset:4608
	ds_read_b128 v[88:91], v215
	ds_read_b128 v[92:95], v232
	ds_read_b128 v[96:99], v232 offset:32
	s_waitcnt lgkmcnt(1)
	v_mfma_f32_32x32x16_bf16 v[116:131], v[92:95], v[88:91], v[116:131]
	v_mfma_f32_32x32x16_bf16 v[100:115], v[84:87], v[88:91], v[100:115]
	ds_read_b128 v[84:87], v232 offset:4640
	ds_read_b128 v[88:91], v215 offset:1024
	s_waitcnt lgkmcnt(0)
	v_mfma_f32_32x32x16_bf16 v[116:131], v[96:99], v[88:91], v[116:131]
	v_exp_f32_e32 v99, v184
	v_add_f32_e32 v184, 0, v68
	v_add_f32_e32 v184, v69, v184
	v_add_f32_e32 v184, v70, v184
	v_add_f32_e32 v184, v71, v184
	v_add_f32_e32 v184, v72, v184
	v_add_f32_e32 v184, v73, v184
	v_mfma_f32_32x32x16_bf16 v[100:115], v[84:87], v[88:91], v[100:115]
	ds_read_b128 v[84:87], v232 offset:64
	ds_read_b128 v[88:91], v232 offset:4672
	ds_read_b128 v[92:95], v215 offset:2048
	v_add_f32_e32 v184, v74, v184
	v_add_f32_e32 v184, v75, v184
	v_add_f32_e32 v184, v76, v184
	v_add_f32_e32 v184, v77, v184
	v_add_f32_e32 v184, v78, v184
	v_add_f32_e32 v184, v79, v184
	s_waitcnt lgkmcnt(0)
	v_mfma_f32_32x32x16_bf16 v[116:131], v[84:87], v[92:95], v[116:131]
	v_add_f32_e32 v184, v80, v184
	v_add_f32_e32 v184, v81, v184
	v_add_f32_e32 v184, v82, v184
	v_add_f32_e32 v184, v83, v184
	v_exp_f32_e32 v96, v197
	v_exp_f32_e32 v97, v198
	v_exp_f32_e32 v98, v199
	v_mfma_f32_32x32x16_bf16 v[100:115], v[88:91], v[92:95], v[100:115]
	ds_read_b128 v[84:87], v232 offset:96
	ds_read_b128 v[88:91], v232 offset:4704
	ds_read_b128 v[92:95], v215 offset:3072
	s_waitcnt lgkmcnt(0)
	v_mfma_f32_32x32x16_bf16 v[116:131], v[84:87], v[92:95], v[116:131]
	v_exp_f32_e32 v84, v185
	v_exp_f32_e32 v85, v186
	v_exp_f32_e32 v86, v187
	v_exp_f32_e32 v87, v188
	v_add_f32_e32 v184, v84, v184
	v_add_f32_e32 v184, v85, v184
	v_add_f32_e32 v184, v86, v184
	v_mfma_f32_32x32x16_bf16 v[100:115], v[88:91], v[92:95], v[100:115]
	v_exp_f32_e32 v88, v189
	v_exp_f32_e32 v89, v190
	v_exp_f32_e32 v90, v191
	v_exp_f32_e32 v91, v192
	v_add_f32_e32 v184, v87, v184
	v_exp_f32_e32 v92, v193
	v_add_f32_e32 v184, v88, v184
	v_exp_f32_e32 v93, v194
	v_add_f32_e32 v184, v89, v184
	v_exp_f32_e32 v94, v195
	v_add_f32_e32 v184, v90, v184
	v_exp_f32_e32 v95, v196
	v_add_f32_e32 v184, v91, v184
	v_add_f32_e32 v184, v92, v184
	v_add_f32_e32 v184, v93, v184
	v_add_f32_e32 v184, v94, v184
	v_add_f32_e32 v184, v95, v184
	v_add_f32_e32 v184, v96, v184
	v_add_f32_e32 v184, v97, v184
	v_add_f32_e32 v184, v98, v184
	v_add_f32_e32 v238, v99, v184
	v_mov_b32_e32 v239, v238
	s_nop 1
	v_permlane32_swap_b32_e32 v238, v239
	v_cvt_pk_bf16_f32 v184, v68, v69
	v_cvt_pk_bf16_f32 v185, v70, v71
	v_cvt_pk_bf16_f32 v186, v72, v73
	v_cvt_pk_bf16_f32 v187, v74, v75
	v_cvt_pk_bf16_f32 v192, v76, v77
	v_cvt_pk_bf16_f32 v193, v78, v79
	v_cvt_pk_bf16_f32 v194, v80, v81
	v_cvt_pk_bf16_f32 v195, v82, v83
	v_cvt_pk_bf16_f32 v196, v84, v85
	v_cvt_pk_bf16_f32 v197, v86, v87
	v_cvt_pk_bf16_f32 v198, v88, v89
	v_cvt_pk_bf16_f32 v199, v90, v91
	v_cvt_pk_bf16_f32 v188, v92, v93
	v_cvt_pk_bf16_f32 v189, v94, v95
	v_cvt_pk_bf16_f32 v190, v96, v97
	v_cvt_pk_bf16_f32 v191, v98, v99
	s_add_i32 s4, s52, 1
	s_cmp_lt_u32 s4, s21
	s_cselect_b64 s[6:7], -1, 0
	s_cmp_ge_u32 s4, s21
	s_cbranch_scc1 .LBB0_376
	s_mov_b32 s25, s45
	s_lshl_b64 s[4:5], s[24:25], 7
	s_add_u32 s54, s86, s4
	s_addc_u32 s55, s87, s5
	s_add_u32 s4, s88, s4
	s_addc_u32 s5, s89, s5
	v_lshl_add_u64 v[164:165], s[4:5], 0, v[200:201]
	v_add_co_u32_e32 v168, vcc, s43, v164
	s_lshl_b64 s[4:5], s[24:25], 6
	s_nop 0
	v_addc_co_u32_e32 v169, vcc, 0, v165, vcc
	v_lshl_add_u64 v[172:173], s[54:55], 0, v[200:201]
	s_add_u32 s4, s90, s4
	v_add_co_u32_e32 v176, vcc, 0x2000, v172
	s_addc_u32 s5, s91, s5
	s_nop 0
	v_addc_co_u32_e32 v177, vcc, 0, v173, vcc
	v_lshl_add_u64 v[180:181], s[4:5], 0, v[210:211]
	global_load_dwordx4 v[164:167], v[164:165], off
	s_nop 0
	global_load_dwordx4 v[168:171], v[168:169], off
	s_nop 0
	global_load_dwordx4 v[172:175], v[172:173], off
	s_nop 0
	global_load_dwordx4 v[176:179], v[176:177], off
	s_nop 0
	global_load_dwordx4 v[180:183], v[180:181], off

; #define SBAR() __builtin_amdgcn_sched_barrier(0)
; #define ACT(t) (KBASE(t) <= qlo + QBLK - 1 && KBASE(t) + KVBLK - 1 >= qlo - W + 1)
; template <int KB, bool SK, bool PE>
; __device__ __forceinline__ void qkt(f32x16& p0, f32x16& p1, const char* lds, int r32, int hi, int wid, int lane, const bf16x8* qr, bool act) {
;     if (SK && !act) { const float NEG = -__builtin_inff();
; #pragma unroll
;         for (int r = 0; r < 16; ++r) { p0[r] = NEG; p1[r] = NEG; } return; }
;     p0 = f32x16{}; p1 = f32x16{};
;     const char* kb[4];
; #pragma unroll
;     for (int dd = 0; dd < 4; ++dd) kb[dd] = lds + OFF_K + KB * SHM_K + KSWZ(r32, (dd * 16 + hi * 8) * 2);
; #pragma unroll
;     for (int d0 = 0; d0 < 8; ++d0) { const char* a = kb[d0 & 3] + (d0 >> 2) * 128;
;         bf16x8 b0 = *reinterpret_cast<const bf16x8*>(a);
;         bf16x8 b1 = *reinterpret_cast<const bf16x8*>(a + 32 * 256);
;         p0 = __builtin_amdgcn_mfma_f32_32x32x16_bf16(b0, qr[d0], p0, 0, 0, 0);
;         p1 = __builtin_amdgcn_mfma_f32_32x32x16_bf16(b1, qr[d0], p1, 0, 0, 0); }
;     if constexpr (PE) {
;         const char* kp = lds + OFF_KPE + KB * SHM_KPE + r32 * KPE_ROW + hi * 16;
;         const char* qp = lds + OFF_QPE + wid * 4096 + lane * 16;
; #pragma unroll
;         for (int d0 = 0; d0 < 4; ++d0) {
;             bf16x8 b0 = *reinterpret_cast<const bf16x8*>(kp + d0 * 32);
;             bf16x8 b1 = *reinterpret_cast<const bf16x8*>(kp + d0 * 32 + 32 * KPE_ROW);
;             bf16x8 qf = *reinterpret_cast<const bf16x8*>(qp + d0 * 1024);
;             p0 = __builtin_amdgcn_mfma_f32_32x32x16_bf16(b0, qf, p0, 0, 0, 0);
;             p1 = __builtin_amdgcn_mfma_f32_32x32x16_bf16(b1, qf, p1, 0, 0, 0); }
;     }
; template <bool PE, bool SK, bool LSE, bool EARLY>
; __device__ __forceinline__ void swa_block(const BlockRef& cur, const BlockRef& nxt, const Prm& P, char* lds, Seam<PE>& S) {
;     ...
;     if (even) { SBAR(); qkt<1, SK, PE>(pB0, pB1, lds, r32, hi, wid, lane, S.qr, ACT(NT - 1)); SBAR(); }
.LBB0_382:
	s_bitcmp0_b32 s21, 0
	s_cselect_b64 s[4:5], -1, 0
	s_and_b64 vcc, exec, s[4:5]
	s_cbranch_vccz .LBB0_384
	ds_read_b128 v[68:71], v222 offset:49152
	ds_read_b128 v[84:87], v222 offset:57344
	ds_read_b128 v[100:103], v221 offset:49152
	ds_read_b128 v[104:107], v221 offset:57344
	s_waitcnt lgkmcnt(3)
	v_mfma_f32_32x32x16_bf16 v[68:83], v[68:71], v[160:163], 0
	s_waitcnt lgkmcnt(2)
	v_mfma_f32_32x32x16_bf16 v[84:99], v[84:87], v[160:163], 0
	s_waitcnt lgkmcnt(1)
	v_mfma_f32_32x32x16_bf16 v[68:83], v[100:103], v[156:159], v[68:83]
	s_waitcnt lgkmcnt(0)
	v_mfma_f32_32x32x16_bf16 v[84:99], v[104:107], v[156:159], v[84:99]
	ds_read_b128 v[100:103], v220 offset:49152
	ds_read_b128 v[104:107], v220 offset:57344
	s_waitcnt lgkmcnt(1)
	v_mfma_f32_32x32x16_bf16 v[68:83], v[100:103], v[152:155], v[68:83]
	s_waitcnt lgkmcnt(0)
	v_mfma_f32_32x32x16_bf16 v[84:99], v[104:107], v[152:155], v[84:99]
	ds_read_b128 v[100:103], v219 offset:49152
	ds_read_b128 v[104:107], v219 offset:57344
	s_waitcnt lgkmcnt(1)
	v_mfma_f32_32x32x16_bf16 v[68:83], v[100:103], v[148:151], v[68:83]
	s_waitcnt lgkmcnt(0)
	v_mfma_f32_32x32x16_bf16 v[84:99], v[104:107], v[148:151], v[84:99]
	v_xor_b32_e32 v222, 0x80, v222
	ds_read_b128 v[100:103], v222 offset:49152
	ds_read_b128 v[104:107], v222 offset:57344
	v_xor_b32_e32 v222, 0x80, v222
	s_waitcnt lgkmcnt(1)
	v_mfma_f32_32x32x16_bf16 v[68:83], v[100:103], v[144:147], v[68:83]
	s_waitcnt lgkmcnt(0)
	v_mfma_f32_32x32x16_bf16 v[84:99], v[104:107], v[144:147], v[84:99]
	v_xor_b32_e32 v221, 0x80, v221
	ds_read_b128 v[100:103], v221 offset:49152
	ds_read_b128 v[104:107], v221 offset:57344
	v_xor_b32_e32 v221, 0x80, v221
	s_waitcnt lgkmcnt(1)
	v_mfma_f32_32x32x16_bf16 v[68:83], v[100:103], v[140:143], v[68:83]
	s_waitcnt lgkmcnt(0)
	v_mfma_f32_32x32x16_bf16 v[84:99], v[104:107], v[140:143], v[84:99]
	v_xor_b32_e32 v220, 0x80, v220
	ds_read_b128 v[100:103], v220 offset:49152
	ds_read_b128 v[104:107], v220 offset:57344
	v_xor_b32_e32 v220, 0x80, v220
	s_waitcnt lgkmcnt(1)
	v_mfma_f32_32x32x16_bf16 v[68:83], v[100:103], v[136:139], v[68:83]
	s_waitcnt lgkmcnt(0)
	v_mfma_f32_32x32x16_bf16 v[84:99], v[104:107], v[136:139], v[84:99]
	v_xor_b32_e32 v219, 0x80, v219
	ds_read_b128 v[100:103], v219 offset:49152
	ds_read_b128 v[104:107], v219 offset:57344
	v_xor_b32_e32 v219, 0x80, v219
	s_waitcnt lgkmcnt(1)
	v_mfma_f32_32x32x16_bf16 v[68:83], v[100:103], v[132:135], v[68:83]
	s_waitcnt lgkmcnt(0)
	v_mfma_f32_32x32x16_bf16 v[84:99], v[104:107], v[132:135], v[84:99]
	ds_read_b128 v[100:103], v233 offset:4608
	ds_read_b128 v[104:107], v215
	ds_read_b128 v[108:111], v233
	ds_read_b128 v[112:115], v233 offset:32
	s_waitcnt lgkmcnt(1)
	v_mfma_f32_32x32x16_bf16 v[68:83], v[108:111], v[104:107], v[68:83]
	v_mfma_f32_32x32x16_bf16 v[84:99], v[100:103], v[104:107], v[84:99]
	ds_read_b128 v[100:103], v233 offset:4640
	ds_read_b128 v[104:107], v215 offset:1024
	s_waitcnt lgkmcnt(0)
	v_mfma_f32_32x32x16_bf16 v[68:83], v[112:115], v[104:107], v[68:83]
	v_mfma_f32_32x32x16_bf16 v[84:99], v[100:103], v[104:107], v[84:99]
	ds_read_b128 v[100:103], v233 offset:64
	ds_read_b128 v[104:107], v233 offset:4672
	ds_read_b128 v[108:111], v215 offset:2048
	s_waitcnt lgkmcnt(0)
	v_mfma_f32_32x32x16_bf16 v[68:83], v[100:103], v[108:111], v[68:83]
	v_mfma_f32_32x32x16_bf16 v[84:99], v[104:107], v[108:111], v[84:99]
	ds_read_b128 v[100:103], v233 offset:96
	ds_read_b128 v[104:107], v233 offset:4704
	ds_read_b128 v[108:111], v215 offset:3072
	s_waitcnt lgkmcnt(0)
	v_mfma_f32_32x32x16_bf16 v[68:83], v[100:103], v[108:111], v[68:83]
	v_mfma_f32_32x32x16_bf16 v[84:99], v[104:107], v[108:111], v[84:99]

; #define VMW() asm volatile("s_waitcnt vmcnt(0)" ::: "memory")
; #define SWRITE_HK(bf) do { *(bf16x8*)(K_lds + (bf) * SHM_K + kws) = S.st_k0; *(bf16x8*)(K_lds + (bf) * SHM_K + kws + 32 * 256) = S.st_k1; \
;                            if constexpr (PE) *(bf16x8*)(lds + OFF_KPE + (bf) * SHM_KPE + pws) = S.st_kp; } while (0)
; template <bool PE>
; __device__ __forceinline__ void swa_prime(const BlockRef& cur, const Prm& P, char* lds, Seam<PE>& S) {
;     int tid_ = threadIdx.x; asm volatile("" : "+v"(tid_));
;     const int tid = tid_, wid = __builtin_amdgcn_readfirstlane(tid >> 6), lane = tid & 63, r32 = lane & 31, hi = lane >> 5;
;     const int sr = tid >> 4, sc = (tid & 15) * 8, kws = KSWZ(sr, sc * 2); char* K_lds = lds + OFF_K;
;     const int pr = tid >> 3, pc = (tid & 7) * 8, pws = pr * KPE_ROW + (tid & 7) * 16;
;     const unsigned kvoff = (unsigned)(sr * P.kvs + sc) * 2u, kpoff = (unsigned)(pr * P.kpes + pc) * 2u, qoff = (unsigned)((wid * QBLK + r32) * P.qs + hi * 8) * 2u, qpoff = (unsigned)((wid * QBLK + r32) * P.qpes + hi * 8) * 2u;
;     const int kb0 = swa_jlo(cur.P0, P.W) * KVBLK;
; #pragma unroll
;     for (int d0 = 0; d0 < 8; ++d0) S.qr[d0] = LDG(cur.Q, qoff + d0 * 32);
;     if constexpr (PE) {
; #pragma unroll
;         for (int d0 = 0; d0 < 4; ++d0) *(bf16x8*)(lds + OFF_QPE + wid * 4096 + d0 * 1024 + lane * 16) = LDG(cur.Qpe, qpoff + d0 * 32);
;     }
;     SLOAD_H(cur, kb0); VMW(); SWRITE_HK(0);
;     __syncthreads();
; }
.LBB0_818:
	s_lshl_b32 s77, s76, 1
	s_sub_i32 s82, 4, s77
	s_ashr_i32 s0, s3, s82
	s_lshl_b32 s1, -1, s82
	s_not_b32 s83, s1
	s_andn2_b32 s9, s3, s1
	s_ashr_i32 s1, s0, 4
	s_sub_i32 s4, 12, s77
	s_ashr_i32 s12, s1, s77
	s_lshl_b32 s1, s1, s4
	s_lshl_b32 s0, s0, 2
	s_and_b32 s13, s1, 0xffe
	s_lshl_b32 s8, s9, 8
	s_mul_i32 s5, s76, 0xc0
	s_and_b32 s21, s0, 60
	s_add_i32 s20, s13, s8
	s_or_b32 s0, s21, s5
	s_ashr_i32 s23, s12, 31
	s_add_u32 s0, s0, s12
	s_addc_u32 s1, 0, s23
	s_lshl_b64 s[0:1], s[0:1], 12
	s_add_u32 s10, s0, s20
	s_addc_u32 s11, s1, 0
	s_lshl_b64 s[10:11], s[10:11], 8
	s_add_u32 s84, s50, s10
	s_addc_u32 s85, s51, s11
	s_or_b32 s0, s0, s13
	s_lshl_b64 s[0:1], s[0:1], 8
	s_add_u32 s90, s7, s0
	s_addc_u32 s91, s73, s1
	s_add_u32 s94, s90, 0x4000000
	s_addc_u32 s95, s91, 0
	s_lshl_b32 s59, s76, 6
	s_or_b32 s0, s21, s59
	s_add_u32 s0, s0, s12
	s_addc_u32 s1, 0, s23
	s_lshl_b64 s[10:11], s[0:1], 12
	s_add_u32 s10, s10, s20
	s_addc_u32 s11, s11, 0
	s_lshl_b64 s[10:11], s[10:11], 8
	s_add_u32 s62, s78, s10
	s_addc_u32 s63, s79, s11
	s_lshl_b64 s[0:1], s[0:1], 14
	s_add_u32 s0, s14, s0
	s_addc_u32 s1, s15, s1
	s_lshl_b32 s10, s20, 2
	v_mov_b32_e32 v3, v0
	s_add_u32 s96, s0, s10
	s_addc_u32 s97, s1, 0
	v_readfirstlane_b32 s0, v3
	s_lshr_b32 s0, s0, 1
	s_and_b32 s0, s0, 0xffffe0
	v_and_or_b32 v4, v3, 31, s0
	s_add_i32 s0, s8, 0xffffff80
	s_cmp_lg_u32 s9, 0
	s_cselect_b32 s44, s0, 0
	v_lshlrev_b32_e32 v9, 4, v3
	s_movk_i32 s0, 0xff00
	v_bitop3_b32 v200, v9, s0, v228 bitop3:0xe0
	s_lshl_b64 s[0:1], s[44:45], 8
	s_add_u32 s10, s90, s0
	v_lshrrev_b32_e32 v5, 1, v3
	s_addc_u32 s11, s91, s1
	v_and_b32_e32 v5, 16, v5
	s_add_u32 s0, s94, s0
	v_lshl_or_b32 v8, v4, 8, v5
	s_addc_u32 s1, s95, s1
	global_load_dwordx4 v[166:169], v8, s[84:85]
	global_load_dwordx4 v[162:165], v8, s[84:85] offset:32
	global_load_dwordx4 v[114:117], v200, s[0:1]
	global_load_dwordx4 v[122:125], v200, s[10:11]
	v_lshl_add_u64 v[4:5], s[0:1], 0, v[200:201]
	v_add_co_u32_e32 v4, vcc, s43, v4
	v_lshl_add_u64 v[6:7], s[10:11], 0, v[200:201]
	s_nop 0
	v_addc_co_u32_e32 v5, vcc, 0, v5, vcc
	v_add_co_u32_e32 v6, vcc, 0x2000, v6
	v_and_b32_e32 v3, 0xf0, v3
	s_nop 0
	v_addc_co_u32_e32 v7, vcc, 0, v7, vcc
	global_load_dwordx4 v[118:121], v[4:5], off
	global_load_dwordx4 v[126:129], v[6:7], off
	global_load_dwordx4 v[174:177], v8, s[84:85] offset:64
	global_load_dwordx4 v[170:173], v8, s[84:85] offset:96
	global_load_dwordx4 v[158:161], v8, s[84:85] offset:128
	global_load_dwordx4 v[154:157], v8, s[84:85] offset:160
	global_load_dwordx4 v[150:153], v8, s[84:85] offset:192
	global_load_dwordx4 v[146:149], v8, s[84:85] offset:224
	s_movk_i32 s0, 0xf0
	s_waitcnt vmcnt(0)
	v_and_b32_e32 v4, 0xffffff00, v9
	v_bitop3_b32 v3, v9, v3, s0 bitop3:0x6c
	s_mov_b32 s75, 0
	v_add3_u32 v3, 0, v4, v3
	s_mov_b32 s0, s8
	s_mov_b64 s[70:71], s[94:95]
	s_mov_b64 s[88:89], s[62:63]
	s_mov_b64 s[86:87], s[96:97]
	s_lshr_b32 s58, 64, s77
	s_mov_b64 s[60:61], s[90:91]
	s_waitcnt vmcnt(8)
	ds_write_b128 v3, v[122:125] offset:32768
	s_waitcnt vmcnt(6)
	ds_write_b128 v3, v[126:129] offset:40960
	s_waitcnt lgkmcnt(0)
	s_barrier
	s_branch .LBB0_820

; #define SBAR() __builtin_amdgcn_sched_barrier(0)
; #define ACT(t) (KBASE(t) <= qlo + QBLK - 1 && KBASE(t) + KVBLK - 1 >= qlo - W + 1)
; template <int KB, bool SK, bool PE>
; __device__ __forceinline__ void qkt(f32x16& p0, f32x16& p1, const char* lds, int r32, int hi, int wid, int lane, const bf16x8* qr, bool act) {
;     if (SK && !act) { const float NEG = -__builtin_inff();
; #pragma unroll
;         for (int r = 0; r < 16; ++r) { p0[r] = NEG; p1[r] = NEG; } return; }
;     p0 = f32x16{}; p1 = f32x16{};
;     const char* kb[4];
; #pragma unroll
;     for (int dd = 0; dd < 4; ++dd) kb[dd] = lds + OFF_K + KB * SHM_K + KSWZ(r32, (dd * 16 + hi * 8) * 2);
; #pragma unroll
;     for (int d0 = 0; d0 < 8; ++d0) { const char* a = kb[d0 & 3] + (d0 >> 2) * 128;
;         bf16x8 b0 = *reinterpret_cast<const bf16x8*>(a);
;         bf16x8 b1 = *reinterpret_cast<const bf16x8*>(a + 32 * 256);
;         p0 = __builtin_amdgcn_mfma_f32_32x32x16_bf16(b0, qr[d0], p0, 0, 0, 0);
;         p1 = __builtin_amdgcn_mfma_f32_32x32x16_bf16(b1, qr[d0], p1, 0, 0, 0); }
; template <bool PE, bool SK, bool LSE, bool EARLY>
; __device__ __forceinline__ void swa_block(const BlockRef& cur, const BlockRef& nxt, const Prm& P, char* lds, Seam<PE>& S) {
;     ...
;     SBAR(); qkt<0, SK, PE>(pA0, pA1, lds, r32, hi, wid, lane, S.qr, ACT(0));
.LBB0_824:
	s_ashr_i32 s52, s9, 1
	s_andn2_b32 s52, s52, 31
	v_and_b32_e32 v213, 31, v50
	v_bfe_u32 v53, v50, 5, 1
	s_add_i32 s20, s52, s8
	s_lshl_b32 s13, s12, 6
	s_or_b32 s21, s20, 31
	s_cmp_gt_i32 s13, s21
	s_cselect_b64 s[8:9], -1, 0
	s_or_b32 s24, s13, 63
	s_add_i32 s42, s20, 0xffffff7f
	s_cmp_le_i32 s24, s42
	s_cselect_b64 s[54:55], -1, 0
	s_or_b64 s[8:9], s[8:9], s[54:55]
	s_and_b64 vcc, exec, s[8:9]
	v_lshlrev_b32_e32 v214, 4, v53
	s_cbranch_vccnz .LBB0_826
	v_lshlrev_b32_e32 v8, 4, v213
	v_and_b32_e32 v3, 8, v213
	v_lshlrev_b32_e32 v3, 4, v3
	v_lshl_or_b32 v3, v213, 8, v3
	v_bitop3_b32 v4, v214, v8, s93 bitop3:0x78
	v_add3_u32 v9, 0, v4, v3
	ds_read_b128 v[4:7], v9 offset:32768
	v_and_b32_e32 v8, 0x70, v8
	v_bitop3_b32 v10, v214, v8, 32 bitop3:0x36
	v_add3_u32 v10, 0, v10, v3
	v_bitop3_b32 v11, v214, v8, 64 bitop3:0x36
	v_add3_u32 v11, 0, v11, v3
	v_bitop3_b32 v8, v214, v8, s16 bitop3:0x36
	v_add3_u32 v3, 0, v8, v3
	s_waitcnt vmcnt(15) lgkmcnt(0)
	v_mfma_f32_32x32x16_bf16 v[34:49], v[4:7], v[166:169], 0
	ds_read_b128 v[4:7], v9 offset:40960
	s_waitcnt lgkmcnt(0)
	v_mfma_f32_32x32x16_bf16 v[18:33], v[4:7], v[166:169], 0
	ds_read_b128 v[4:7], v10 offset:32768
	s_waitcnt vmcnt(14) lgkmcnt(0)
	v_mfma_f32_32x32x16_bf16 v[34:49], v[4:7], v[162:165], v[34:49]
	ds_read_b128 v[4:7], v10 offset:40960
	s_waitcnt lgkmcnt(0)
	v_mfma_f32_32x32x16_bf16 v[18:33], v[4:7], v[162:165], v[18:33]
	ds_read_b128 v[4:7], v11 offset:32768
	s_waitcnt vmcnt(5) lgkmcnt(0)
	v_mfma_f32_32x32x16_bf16 v[34:49], v[4:7], v[174:177], v[34:49]
	ds_read_b128 v[4:7], v11 offset:40960
	s_waitcnt lgkmcnt(0)
	v_mfma_f32_32x32x16_bf16 v[18:33], v[4:7], v[174:177], v[18:33]
	ds_read_b128 v[4:7], v3 offset:32768
	s_waitcnt vmcnt(4) lgkmcnt(0)
	v_mfma_f32_32x32x16_bf16 v[34:49], v[4:7], v[170:173], v[34:49]
	ds_read_b128 v[4:7], v3 offset:40960
	s_waitcnt lgkmcnt(0)
	v_mfma_f32_32x32x16_bf16 v[18:33], v[4:7], v[170:173], v[18:33]
	v_xor_b32_e32 v9, 0x80, v9
	ds_read_b128 v[4:7], v9 offset:32768
	s_waitcnt vmcnt(3) lgkmcnt(0)
	v_mfma_f32_32x32x16_bf16 v[34:49], v[4:7], v[158:161], v[34:49]
	ds_read_b128 v[4:7], v9 offset:40960
	v_xor_b32_e32 v9, 0x80, v9
	s_waitcnt lgkmcnt(0)
	v_mfma_f32_32x32x16_bf16 v[18:33], v[4:7], v[158:161], v[18:33]
	v_xor_b32_e32 v10, 0x80, v10
	ds_read_b128 v[4:7], v10 offset:32768
	s_waitcnt vmcnt(2) lgkmcnt(0)
	v_mfma_f32_32x32x16_bf16 v[34:49], v[4:7], v[154:157], v[34:49]
	ds_read_b128 v[4:7], v10 offset:40960
	v_xor_b32_e32 v10, 0x80, v10
	s_waitcnt lgkmcnt(0)
	v_mfma_f32_32x32x16_bf16 v[18:33], v[4:7], v[154:157], v[18:33]
	v_xor_b32_e32 v11, 0x80, v11
	ds_read_b128 v[4:7], v11 offset:32768
	s_waitcnt vmcnt(1) lgkmcnt(0)
	v_mfma_f32_32x32x16_bf16 v[34:49], v[4:7], v[150:153], v[34:49]
	ds_read_b128 v[4:7], v11 offset:40960
	v_xor_b32_e32 v11, 0x80, v11
	s_waitcnt lgkmcnt(0)
	v_mfma_f32_32x32x16_bf16 v[18:33], v[4:7], v[150:153], v[18:33]
	v_xor_b32_e32 v3, 0x80, v3
	ds_read_b128 v[4:7], v3 offset:32768
	s_waitcnt vmcnt(0) lgkmcnt(0)
	v_mfma_f32_32x32x16_bf16 v[34:49], v[4:7], v[146:149], v[34:49]
	ds_read_b128 v[4:7], v3 offset:40960
	v_xor_b32_e32 v3, 0x80, v3
	s_waitcnt lgkmcnt(0)
	v_mfma_f32_32x32x16_bf16 v[18:33], v[4:7], v[146:149], v[18:33]
	s_branch .LBB0_827

; #define SBAR() __builtin_amdgcn_sched_barrier(0)
; #define VMW() asm volatile("s_waitcnt vmcnt(0)" ::: "memory")
; #define SWRITE_H(bf) do { SWRITE_HV(bf); SWRITE_HK(bf); } while (0)
; #define ACT(t) (KBASE(t) <= qlo + QBLK - 1 && KBASE(t) + KVBLK - 1 >= qlo - W + 1)
; #define MASKT(P0_, P1_, t) do { const int kb_ = KBASE(t); if ((!SK || ACT(t)) && (kb_ + KVBLK - 1 > qlo || kb_ <= qlo + QBLK - 1 - W)) mask_tile(P0_, P1_, qm - kb_, (unsigned)W); } while (0)
; __device__ __forceinline__ void partialSM(f32x16& p0, f32x16& p1, float& m_reg, float& mn, float& alpha, const float scale) {
;     float pmax = p0[0]; for (int r = 1; r < 16; ++r) pmax = fmaxf(pmax, p0[r]); for (int r = 0; r < 16; ++r) pmax = fmaxf(pmax, p1[r]);
;     { auto rr = __builtin_amdgcn_permlane32_swap(__float_as_uint(pmax), __float_as_uint(pmax), false, false);
;       pmax = fmaxf(__uint_as_float(rr[0]), __uint_as_float(rr[1])); }
;     const float C2 = 1.4426950408889634f * scale;
;     if (__builtin_expect(__all((pmax - m_reg) * scale <= THR), 1)) { mn = m_reg; alpha = 1.f; }
;     else { mn = fmaxf(m_reg, pmax); alpha = __builtin_amdgcn_exp2f((m_reg - mn) * C2); m_reg = mn; }
;     const float mnL = -mn * C2;
;     for (int r = 0; r < 16; ++r) p0[r] = fmaf(p0[r], C2, mnL); for (int r = 0; r < 16; ++r) p1[r] = fmaf(p1[r], C2, mnL);
;     for (int r = 0; r < 16; ++r) p0[r] = __builtin_amdgcn_exp2f(p0[r]);
; }
; template <bool PE, bool SK, bool LSE, bool EARLY>
; __device__ __forceinline__ void swa_block(const BlockRef& cur, const BlockRef& nxt, const Prm& P, char* lds, Seam<PE>& S) {
;     ...
;     SBAR(); qkt<0, SK, PE>(pA0, pA1, lds, r32, hi, wid, lane, S.qr, ACT(0));
;     MASKT(pA0, pA1, 0); partialSM(pA0, pA1, m_reg, mnA, alA, P.scale);
;     if (NT > 1) { VMW(); SWRITE_H(1); }
;     __syncthreads();
;     ...
;     for (int t = 1; t + 1 < NT; t += 2) {
;         HALF_STEP(pB0, pB1, mnB, alB, pA0, pA1, alA, t, 1, 0, 0);
;         HALF_STEP(pA0, pA1, mnA, alA, pB0, pB1, alB, t + 1, 0, 1, 1);
.LBB0_830:
	v_and_b32_e32 v4, 0xf0, v50
	v_bitop3_b32 v5, v51, v52, v4 bitop3:0xde
	v_max_f32_e32 v4, v35, v35
	v_max_f32_e32 v6, v34, v34
	v_max_f32_e32 v4, v6, v4
	v_max3_f32 v4, v4, v36, v37
	v_max3_f32 v4, v4, v38, v39
	v_max3_f32 v4, v4, v40, v41
	v_max3_f32 v4, v4, v42, v43
	v_max3_f32 v4, v4, v44, v45
	v_max3_f32 v4, v4, v46, v47
	v_max3_f32 v4, v4, v48, v49
	v_max3_f32 v4, v4, v18, v19
	v_max3_f32 v4, v4, v20, v21
	v_max3_f32 v4, v4, v22, v23
	v_max3_f32 v4, v4, v24, v25
	v_max3_f32 v4, v4, v26, v27
	v_max3_f32 v4, v4, v28, v29
	v_max3_f32 v4, v4, v30, v31
	v_max3_f32 v4, v4, v32, v33
	v_mov_b32_e32 v6, v4
	s_nop 1
	v_permlane32_swap_b32_e32 v4, v6
	v_max_f32_e32 v6, v6, v6
	v_max_f32_e32 v4, v4, v4
	v_max_f32_e32 v4, v4, v6
	v_add_f32_e32 v6, 0x7149f2ca, v4
	v_mul_f32_e32 v6, 0x3db504f3, v6
	v_cmp_ge_f32_e32 vcc, s35, v6
	s_cmp_eq_u64 vcc, exec
	s_cselect_b64 s[8:9], -1, 0
	s_andn2_b64 vcc, exec, s[10:11]
	v_add_u32_e32 v210, 0, v5
	s_cbranch_vccnz .LBB0_832
	s_waitcnt vmcnt(0)
	s_waitcnt vmcnt(3)
	ds_write_b128 v215, v[114:117] offset:16384
	s_waitcnt vmcnt(2)
	ds_write_b128 v216, v[118:121] offset:16384
	s_waitcnt vmcnt(1)
	ds_write_b128 v210, v[122:125] offset:49152
	s_waitcnt vmcnt(0)
	ds_write_b128 v210, v[126:129] offset:57344
.LBB0_832:
	v_max_f32_e32 v5, 0xf149f2ca, v4
	v_cndmask_b32_e64 v195, v5, v229, s[8:9]
	v_sub_f32_e32 v5, 0xf149f2ca, v5
	v_mul_f32_e32 v5, 0x3e0293ee, v5
	v_exp_f32_e32 v5, v5
	v_and_b32_e32 v199, 63, v50
	v_mul_f32_e32 v4, 0xbe0293ee, v195
	v_fmamk_f32 v6, v34, 0x3e0293ee, v4
	v_cndmask_b32_e64 v194, v5, 1.0, s[8:9]
	v_pk_fma_f32 v[130:131], v[32:33], s[64:65], v[4:5] op_sel_hi:[1,0,0]
	v_pk_fma_f32 v[132:133], v[30:31], s[64:65], v[4:5] op_sel_hi:[1,0,0]
	v_pk_fma_f32 v[134:135], v[28:29], s[64:65], v[4:5] op_sel_hi:[1,0,0]
	v_pk_fma_f32 v[136:137], v[26:27], s[64:65], v[4:5] op_sel_hi:[1,0,0]
	v_pk_fma_f32 v[138:139], v[24:25], s[64:65], v[4:5] op_sel_hi:[1,0,0]
	v_pk_fma_f32 v[140:141], v[22:23], s[64:65], v[4:5] op_sel_hi:[1,0,0]
	v_pk_fma_f32 v[142:143], v[20:21], s[64:65], v[4:5] op_sel_hi:[1,0,0]
	v_pk_fma_f32 v[144:145], v[18:19], s[64:65], v[4:5] op_sel_hi:[1,0,0]
	v_lshlrev_b32_e32 v5, 4, v199
	v_fmamk_f32 v7, v35, 0x3e0293ee, v4
	v_fmamk_f32 v8, v36, 0x3e0293ee, v4
	v_fmamk_f32 v9, v37, 0x3e0293ee, v4
	v_fmamk_f32 v10, v38, 0x3e0293ee, v4
	v_fmamk_f32 v11, v39, 0x3e0293ee, v4
	v_fmamk_f32 v12, v40, 0x3e0293ee, v4
	v_fmamk_f32 v13, v41, 0x3e0293ee, v4
	v_fmamk_f32 v14, v42, 0x3e0293ee, v4
	v_fmamk_f32 v15, v43, 0x3e0293ee, v4
	v_fmamk_f32 v16, v44, 0x3e0293ee, v4
	v_fmamk_f32 v17, v45, 0x3e0293ee, v4
	v_fmamk_f32 v34, v46, 0x3e0293ee, v4
	v_fmamk_f32 v35, v47, 0x3e0293ee, v4
	v_fmamk_f32 v36, v48, 0x3e0293ee, v4
	v_fmamk_f32 v37, v49, 0x3e0293ee, v4
	v_lshlrev_b32_e32 v4, 3, v199
	v_and_b32_e32 v5, 0xc0, v5
	v_exp_f32_e32 v239, v6
	v_exp_f32_e32 v241, v7
	v_exp_f32_e32 v237, v8
	v_exp_f32_e32 v240, v9
	v_exp_f32_e32 v234, v10
	v_exp_f32_e32 v238, v11
	v_exp_f32_e32 v225, v12
	v_exp_f32_e32 v235, v13
	v_exp_f32_e32 v222, v14
	v_exp_f32_e32 v232, v15
	v_exp_f32_e32 v198, v16
	v_exp_f32_e32 v223, v17
	v_exp_f32_e32 v197, v34
	v_exp_f32_e32 v236, v35
	v_exp_f32_e32 v224, v36
	v_exp_f32_e32 v233, v37
	v_and_or_b32 v4, v4, 24, v5
	v_lshlrev_b32_e32 v5, 1, v199
	v_lshlrev_b32_e32 v6, 6, v199
	v_and_b32_e32 v5, 32, v5
	v_and_b32_e32 v6, 0x800, v6
	s_cmp_lg_u32 0, -1
	v_or3_b32 v4, v4, v5, v6
	s_cselect_b32 s8, 0, 0
	v_add_u32_e32 v211, s8, v4
	s_cmp_lt_i32 s23, 3
	s_waitcnt lgkmcnt(0)
	s_barrier
	s_cbranch_scc1 .LBB0_859
	v_lshlrev_b32_e32 v5, 4, v213
	v_and_b32_e32 v5, 0x70, v5
	v_or_b32_e32 v7, 32, v214
	v_or_b32_e32 v8, 64, v214
	v_or_b32_e32 v9, 0x60, v214
	s_add_i32 s8, s20, 0xffffff45
	v_xad_u32 v6, v214, v5, 0
	v_xad_u32 v7, v7, v5, 0
	v_xad_u32 v8, v8, v5, 0
	v_xad_u32 v5, v9, v5, 0
	v_add_u32_e32 v9, s8, v213
	v_mov_b32_e32 v32, v201
	v_mov_b32_e32 v33, v201
	v_and_b32_e32 v4, 8, v213
	v_lshlrev_b32_e32 v4, 4, v4
	v_lshl_or_b32 v4, v213, 8, v4
	v_sub_u32_e32 v3, v9, v3
	s_lshl_b32 s8, s12, 7
	v_mov_b32_e32 v18, v201
	v_mov_b32_e32 v19, v201
	v_mov_b32_e32 v20, v201
	v_mov_b32_e32 v21, v201
	v_mov_b32_e32 v22, v201
	v_mov_b32_e32 v23, v201
	v_mov_b32_e32 v24, v201
	v_mov_b32_e32 v25, v201
	v_mov_b32_e32 v26, v201
	v_mov_b32_e32 v27, v201
	v_mov_b32_e32 v28, v201
	v_mov_b32_e32 v29, v201
	v_mov_b32_e32 v30, v201
	v_mov_b32_e32 v31, v201
	v_mov_b64_e32 v[48:49], v[32:33]
	v_mov_b64_e32 v[64:65], v[32:33]
	v_mov_b64_e32 v[80:81], v[32:33]
	s_add_i32 s53, s20, 0xffffff9e
	s_add_i32 s54, s13, 0xbf
	v_subrev_u32_e32 v217, s13, v3
	s_add_i32 s24, s8, 0x180
	v_mov_b32_e32 v196, 0
	s_mov_b32 s55, 2
	v_add_u32_e32 v218, v6, v4
	v_add_u32_e32 v219, v7, v4
	v_add_u32_e32 v220, v8, v4
	v_add_u32_e32 v221, v5, v4
	v_mov_b64_e32 v[46:47], v[30:31]
	v_mov_b64_e32 v[44:45], v[28:29]
	v_mov_b64_e32 v[42:43], v[26:27]
	v_mov_b64_e32 v[40:41], v[24:25]
	v_mov_b64_e32 v[38:39], v[22:23]
	v_mov_b64_e32 v[36:37], v[20:21]
	v_mov_b64_e32 v[34:35], v[18:19]
	v_mov_b64_e32 v[62:63], v[30:31]
	v_mov_b64_e32 v[60:61], v[28:29]
	v_mov_b64_e32 v[58:59], v[26:27]
	v_mov_b64_e32 v[56:57], v[24:25]
	v_mov_b64_e32 v[54:55], v[22:23]
	v_mov_b64_e32 v[52:53], v[20:21]
	v_mov_b64_e32 v[50:51], v[18:19]
	v_mov_b64_e32 v[78:79], v[30:31]
	v_mov_b64_e32 v[76:77], v[28:29]
	v_mov_b64_e32 v[74:75], v[26:27]
	v_mov_b64_e32 v[72:73], v[24:25]
	v_mov_b64_e32 v[70:71], v[22:23]
	v_mov_b64_e32 v[68:69], v[20:21]
	v_mov_b64_e32 v[66:67], v[18:19]
	s_branch .LBB0_835

; template <int KB, bool SK, bool PE>
; __device__ __forceinline__ void qkt(f32x16& p0, f32x16& p1, const char* lds, int r32, int hi, int wid, int lane, const bf16x8* qr, bool act) {
;     if (SK && !act) { const float NEG = -__builtin_inff();
; #pragma unroll
;         for (int r = 0; r < 16; ++r) { p0[r] = NEG; p1[r] = NEG; } return; }
;     p0 = f32x16{}; p1 = f32x16{};
;     const char* kb[4];
; #pragma unroll
;     for (int dd = 0; dd < 4; ++dd) kb[dd] = lds + OFF_K + KB * SHM_K + KSWZ(r32, (dd * 16 + hi * 8) * 2);
; #pragma unroll
;     for (int d0 = 0; d0 < 8; ++d0) { const char* a = kb[d0 & 3] + (d0 >> 2) * 128;
;         bf16x8 b0 = *reinterpret_cast<const bf16x8*>(a);
;         bf16x8 b1 = *reinterpret_cast<const bf16x8*>(a + 32 * 256);
;         p0 = __builtin_amdgcn_mfma_f32_32x32x16_bf16(b0, qr[d0], p0, 0, 0, 0);
;         p1 = __builtin_amdgcn_mfma_f32_32x32x16_bf16(b1, qr[d0], p1, 0, 0, 0); }
.LBB0_835:
	s_sub_i32 s44, s54, 63
	s_lshl_b64 s[8:9], s[44:45], 8
	s_add_u32 s10, s90, s8
	s_addc_u32 s11, s91, s9
	s_add_u32 s8, s94, s8
	s_addc_u32 s9, s95, s9
	v_lshl_add_u64 v[4:5], s[8:9], 0, v[200:201]
	v_add_co_u32_e32 v6, vcc, s43, v4
	s_nop 1
	v_addc_co_u32_e32 v7, vcc, 0, v5, vcc
	global_load_dwordx4 v[178:181], v[4:5], off
	global_load_dwordx4 v[182:185], v[6:7], off
	v_lshl_add_u64 v[4:5], s[10:11], 0, v[200:201]
	v_add_co_u32_e32 v6, vcc, 0x2000, v4
	s_nop 1
	v_addc_co_u32_e32 v7, vcc, 0, v5, vcc
	global_load_dwordx4 v[186:189], v[4:5], off
	global_load_dwordx4 v[190:193], v[6:7], off
	s_add_i32 s10, s54, 0xffffff81
	s_cmp_gt_i32 s10, s21
	s_cselect_b64 s[8:9], -1, 0
	s_sub_i32 s11, s54, 64
	s_cmp_le_i32 s11, s42
	s_cselect_b64 s[12:13], -1, 0
	s_or_b64 s[8:9], s[8:9], s[12:13]
	s_and_b64 vcc, exec, s[8:9]
	s_cbranch_vccnz .LBB0_837
	ds_read_b128 v[4:7], v218 offset:49152
	s_waitcnt vmcnt(19) lgkmcnt(0)
	v_mfma_f32_32x32x16_bf16 v[98:113], v[4:7], v[166:169], 0
	ds_read_b128 v[4:7], v218 offset:57344
	s_waitcnt lgkmcnt(0)
	v_mfma_f32_32x32x16_bf16 v[82:97], v[4:7], v[166:169], 0
	ds_read_b128 v[4:7], v219 offset:49152
	s_waitcnt vmcnt(18) lgkmcnt(0)
	v_mfma_f32_32x32x16_bf16 v[98:113], v[4:7], v[162:165], v[98:113]
	ds_read_b128 v[4:7], v219 offset:57344
	s_waitcnt lgkmcnt(0)
	v_mfma_f32_32x32x16_bf16 v[82:97], v[4:7], v[162:165], v[82:97]
	ds_read_b128 v[4:7], v220 offset:49152
	s_waitcnt vmcnt(9) lgkmcnt(0)
	v_mfma_f32_32x32x16_bf16 v[98:113], v[4:7], v[174:177], v[98:113]
	ds_read_b128 v[4:7], v220 offset:57344
	s_waitcnt lgkmcnt(0)
	v_mfma_f32_32x32x16_bf16 v[82:97], v[4:7], v[174:177], v[82:97]
	ds_read_b128 v[4:7], v221 offset:49152
	s_waitcnt vmcnt(8) lgkmcnt(0)
	v_mfma_f32_32x32x16_bf16 v[98:113], v[4:7], v[170:173], v[98:113]
	ds_read_b128 v[4:7], v221 offset:57344
	s_waitcnt lgkmcnt(0)
	v_mfma_f32_32x32x16_bf16 v[82:97], v[4:7], v[170:173], v[82:97]
	v_xor_b32_e32 v218, 0x80, v218
	ds_read_b128 v[4:7], v218 offset:49152
	s_waitcnt vmcnt(7) lgkmcnt(0)
	v_mfma_f32_32x32x16_bf16 v[98:113], v[4:7], v[158:161], v[98:113]
	ds_read_b128 v[4:7], v218 offset:57344
	v_xor_b32_e32 v218, 0x80, v218
	s_waitcnt lgkmcnt(0)
	v_mfma_f32_32x32x16_bf16 v[82:97], v[4:7], v[158:161], v[82:97]
	v_xor_b32_e32 v219, 0x80, v219
	ds_read_b128 v[4:7], v219 offset:49152
	s_waitcnt vmcnt(6) lgkmcnt(0)
	v_mfma_f32_32x32x16_bf16 v[98:113], v[4:7], v[154:157], v[98:113]
	ds_read_b128 v[4:7], v219 offset:57344
	v_xor_b32_e32 v219, 0x80, v219
	s_waitcnt lgkmcnt(0)
	v_mfma_f32_32x32x16_bf16 v[82:97], v[4:7], v[154:157], v[82:97]
	v_xor_b32_e32 v220, 0x80, v220
	ds_read_b128 v[4:7], v220 offset:49152
	s_waitcnt vmcnt(5) lgkmcnt(0)
	v_mfma_f32_32x32x16_bf16 v[98:113], v[4:7], v[150:153], v[98:113]
	ds_read_b128 v[4:7], v220 offset:57344
	v_xor_b32_e32 v220, 0x80, v220
	s_waitcnt lgkmcnt(0)
	v_mfma_f32_32x32x16_bf16 v[82:97], v[4:7], v[150:153], v[82:97]
	v_xor_b32_e32 v221, 0x80, v221
	ds_read_b128 v[4:7], v221 offset:49152
	s_waitcnt vmcnt(4) lgkmcnt(0)
	v_mfma_f32_32x32x16_bf16 v[98:113], v[4:7], v[146:149], v[98:113]
	ds_read_b128 v[4:7], v221 offset:57344
	v_xor_b32_e32 v221, 0x80, v221
	s_waitcnt lgkmcnt(0)
	v_mfma_f32_32x32x16_bf16 v[82:97], v[4:7], v[146:149], v[82:97]
	s_branch .LBB0_838

; template <int KB, bool SK, bool PE>
; __device__ __forceinline__ void qkt(f32x16& p0, f32x16& p1, const char* lds, int r32, int hi, int wid, int lane, const bf16x8* qr, bool act) {
;     if (SK && !act) { const float NEG = -__builtin_inff();
; #pragma unroll
;         for (int r = 0; r < 16; ++r) { p0[r] = NEG; p1[r] = NEG; } return; }
;     p0 = f32x16{}; p1 = f32x16{};
;     const char* kb[4];
; #pragma unroll
;     for (int dd = 0; dd < 4; ++dd) kb[dd] = lds + OFF_K + KB * SHM_K + KSWZ(r32, (dd * 16 + hi * 8) * 2);
; #pragma unroll
;     for (int d0 = 0; d0 < 8; ++d0) { const char* a = kb[d0 & 3] + (d0 >> 2) * 128;
;         bf16x8 b0 = *reinterpret_cast<const bf16x8*>(a);
;         bf16x8 b1 = *reinterpret_cast<const bf16x8*>(a + 32 * 256);
;         p0 = __builtin_amdgcn_mfma_f32_32x32x16_bf16(b0, qr[d0], p0, 0, 0, 0);
;         p1 = __builtin_amdgcn_mfma_f32_32x32x16_bf16(b1, qr[d0], p1, 0, 0, 0); }
.LBB0_847:
	s_cmp_gt_i32 s44, s21
	s_cselect_b64 s[48:49], -1, 0
	s_cmp_le_i32 s54, s42
	s_cselect_b64 s[68:69], -1, 0
	s_or_b64 s[68:69], s[48:49], s[68:69]
	s_and_b64 vcc, exec, s[68:69]
	s_cbranch_vccnz .LBB0_849
	ds_read_b128 v[4:7], v218 offset:32768
	s_waitcnt lgkmcnt(0)
	v_mfma_f32_32x32x16_bf16 v[130:145], v[4:7], v[166:169], 0
	ds_read_b128 v[4:7], v218 offset:40960
	s_waitcnt lgkmcnt(0)
	v_mfma_f32_32x32x16_bf16 v[114:129], v[4:7], v[166:169], 0
	ds_read_b128 v[4:7], v219 offset:32768
	s_waitcnt lgkmcnt(0)
	v_mfma_f32_32x32x16_bf16 v[130:145], v[4:7], v[162:165], v[130:145]
	ds_read_b128 v[4:7], v219 offset:40960
	s_waitcnt lgkmcnt(0)
	v_mfma_f32_32x32x16_bf16 v[114:129], v[4:7], v[162:165], v[114:129]
	ds_read_b128 v[4:7], v220 offset:32768
	s_waitcnt lgkmcnt(0)
	v_mfma_f32_32x32x16_bf16 v[130:145], v[4:7], v[174:177], v[130:145]
	ds_read_b128 v[4:7], v220 offset:40960
	s_waitcnt lgkmcnt(0)
	v_mfma_f32_32x32x16_bf16 v[114:129], v[4:7], v[174:177], v[114:129]
	ds_read_b128 v[4:7], v221 offset:32768
	s_waitcnt lgkmcnt(0)
	v_mfma_f32_32x32x16_bf16 v[130:145], v[4:7], v[170:173], v[130:145]
	ds_read_b128 v[4:7], v221 offset:40960
	s_waitcnt lgkmcnt(0)
	v_mfma_f32_32x32x16_bf16 v[114:129], v[4:7], v[170:173], v[114:129]
	v_xor_b32_e32 v218, 0x80, v218
	ds_read_b128 v[4:7], v218 offset:32768
	s_waitcnt lgkmcnt(0)
	v_mfma_f32_32x32x16_bf16 v[130:145], v[4:7], v[158:161], v[130:145]
	ds_read_b128 v[4:7], v218 offset:40960
	v_xor_b32_e32 v218, 0x80, v218
	s_waitcnt lgkmcnt(0)
	v_mfma_f32_32x32x16_bf16 v[114:129], v[4:7], v[158:161], v[114:129]
	v_xor_b32_e32 v219, 0x80, v219
	ds_read_b128 v[4:7], v219 offset:32768
	s_waitcnt lgkmcnt(0)
	v_mfma_f32_32x32x16_bf16 v[130:145], v[4:7], v[154:157], v[130:145]
	ds_read_b128 v[4:7], v219 offset:40960
	v_xor_b32_e32 v219, 0x80, v219
	s_waitcnt lgkmcnt(0)
	v_mfma_f32_32x32x16_bf16 v[114:129], v[4:7], v[154:157], v[114:129]
	v_xor_b32_e32 v220, 0x80, v220
	ds_read_b128 v[4:7], v220 offset:32768
	s_waitcnt lgkmcnt(0)
	v_mfma_f32_32x32x16_bf16 v[130:145], v[4:7], v[150:153], v[130:145]
	ds_read_b128 v[4:7], v220 offset:40960
	v_xor_b32_e32 v220, 0x80, v220
	s_waitcnt lgkmcnt(0)
	v_mfma_f32_32x32x16_bf16 v[114:129], v[4:7], v[150:153], v[114:129]
	v_xor_b32_e32 v221, 0x80, v221
	ds_read_b128 v[4:7], v221 offset:32768
	s_waitcnt lgkmcnt(0)
	v_mfma_f32_32x32x16_bf16 v[130:145], v[4:7], v[146:149], v[130:145]
	ds_read_b128 v[4:7], v221 offset:40960
	v_xor_b32_e32 v221, 0x80, v221
	s_waitcnt lgkmcnt(0)
	v_mfma_f32_32x32x16_bf16 v[114:129], v[4:7], v[146:149], v[114:129]
	s_branch .LBB0_850

; #define SBAR() __builtin_amdgcn_sched_barrier(0)
; #define ACT(t) (KBASE(t) <= qlo + QBLK - 1 && KBASE(t) + KVBLK - 1 >= qlo - W + 1)
; template <int KB, bool SK, bool PE>
; __device__ __forceinline__ void qkt(f32x16& p0, f32x16& p1, const char* lds, int r32, int hi, int wid, int lane, const bf16x8* qr, bool act) {
;     if (SK && !act) { const float NEG = -__builtin_inff();
; #pragma unroll
;         for (int r = 0; r < 16; ++r) { p0[r] = NEG; p1[r] = NEG; } return; }
;     p0 = f32x16{}; p1 = f32x16{};
;     const char* kb[4];
; #pragma unroll
;     for (int dd = 0; dd < 4; ++dd) kb[dd] = lds + OFF_K + KB * SHM_K + KSWZ(r32, (dd * 16 + hi * 8) * 2);
; #pragma unroll
;     for (int d0 = 0; d0 < 8; ++d0) { const char* a = kb[d0 & 3] + (d0 >> 2) * 128;
;         bf16x8 b0 = *reinterpret_cast<const bf16x8*>(a);
;         bf16x8 b1 = *reinterpret_cast<const bf16x8*>(a + 32 * 256);
;         p0 = __builtin_amdgcn_mfma_f32_32x32x16_bf16(b0, qr[d0], p0, 0, 0, 0);
;         p1 = __builtin_amdgcn_mfma_f32_32x32x16_bf16(b1, qr[d0], p1, 0, 0, 0); }
; template <bool PE, bool SK, bool LSE, bool EARLY>
; __device__ __forceinline__ void swa_block(const BlockRef& cur, const BlockRef& nxt, const Prm& P, char* lds, Seam<PE>& S) {
;     ...
;     if (even) { SBAR(); qkt<1, SK, PE>(pB0, pB1, lds, r32, hi, wid, lane, S.qr, ACT(NT - 1)); SBAR(); }
.LBB0_860:
	s_bitcmp0_b32 s23, 0
	s_cselect_b64 s[8:9], -1, 0
	s_and_b64 vcc, exec, s[8:9]
	s_cbranch_vccz .LBB0_865
	s_lshl_b32 s12, s1, 6
	s_sub_i32 s10, s12, 64
	s_cmp_le_i32 s10, s21
	s_cselect_b64 s[10:11], -1, 0
	s_add_i32 s13, s20, 0xffffff80
	s_cmp_gt_i32 s12, s13
	s_cselect_b64 s[12:13], -1, 0
	s_and_b64 s[10:11], s[10:11], s[12:13]
	s_andn2_b64 vcc, exec, s[10:11]
	s_cbranch_vccnz .LBB0_863
	v_lshlrev_b32_e32 v4, 4, v213
	v_and_b32_e32 v3, 8, v213
	v_lshlrev_b32_e32 v3, 4, v3
	v_lshl_or_b32 v3, v213, 8, v3
	v_and_b32_e32 v5, 0x70, v4
	v_bitop3_b32 v4, v214, v4, s93 bitop3:0x78
	v_add3_u32 v12, 0, v4, v3
	v_bitop3_b32 v4, v214, v5, 32 bitop3:0x36
	v_add3_u32 v13, 0, v4, v3
	v_bitop3_b32 v4, v214, v5, 64 bitop3:0x36
	v_add3_u32 v14, 0, v4, v3
	v_bitop3_b32 v4, v214, v5, s16 bitop3:0x36
	v_add3_u32 v3, 0, v4, v3
	ds_read_b128 v[4:7], v12 offset:49152
	ds_read_b128 v[8:11], v12 offset:57344
	s_waitcnt vmcnt(15) lgkmcnt(1)
	v_mfma_f32_32x32x16_bf16 v[82:97], v[4:7], v[166:169], 0
	s_waitcnt lgkmcnt(0)
	v_mfma_f32_32x32x16_bf16 v[98:113], v[8:11], v[166:169], 0
	ds_read_b128 v[4:7], v13 offset:49152
	ds_read_b128 v[8:11], v13 offset:57344
	s_waitcnt vmcnt(14) lgkmcnt(1)
	v_mfma_f32_32x32x16_bf16 v[82:97], v[4:7], v[162:165], v[82:97]
	s_waitcnt lgkmcnt(0)
	v_mfma_f32_32x32x16_bf16 v[98:113], v[8:11], v[162:165], v[98:113]
	ds_read_b128 v[4:7], v14 offset:49152
	ds_read_b128 v[8:11], v14 offset:57344
	s_waitcnt vmcnt(5) lgkmcnt(1)
	v_mfma_f32_32x32x16_bf16 v[82:97], v[4:7], v[174:177], v[82:97]
	s_waitcnt lgkmcnt(0)
	v_mfma_f32_32x32x16_bf16 v[98:113], v[8:11], v[174:177], v[98:113]
	ds_read_b128 v[4:7], v3 offset:49152
	ds_read_b128 v[8:11], v3 offset:57344
	s_waitcnt vmcnt(4) lgkmcnt(1)
	v_mfma_f32_32x32x16_bf16 v[82:97], v[4:7], v[170:173], v[82:97]
	s_waitcnt lgkmcnt(0)
	v_mfma_f32_32x32x16_bf16 v[98:113], v[8:11], v[170:173], v[98:113]
	v_xor_b32_e32 v12, 0x80, v12
	ds_read_b128 v[4:7], v12 offset:49152
	ds_read_b128 v[8:11], v12 offset:57344
	v_xor_b32_e32 v12, 0x80, v12
	s_waitcnt vmcnt(3) lgkmcnt(1)
	v_mfma_f32_32x32x16_bf16 v[82:97], v[4:7], v[158:161], v[82:97]
	s_waitcnt lgkmcnt(0)
	v_mfma_f32_32x32x16_bf16 v[98:113], v[8:11], v[158:161], v[98:113]
	v_xor_b32_e32 v13, 0x80, v13
	ds_read_b128 v[4:7], v13 offset:49152
	ds_read_b128 v[8:11], v13 offset:57344
	v_xor_b32_e32 v13, 0x80, v13
	s_waitcnt vmcnt(2) lgkmcnt(1)
	v_mfma_f32_32x32x16_bf16 v[82:97], v[4:7], v[154:157], v[82:97]
	s_waitcnt lgkmcnt(0)
	v_mfma_f32_32x32x16_bf16 v[98:113], v[8:11], v[154:157], v[98:113]
	v_xor_b32_e32 v14, 0x80, v14
	ds_read_b128 v[4:7], v14 offset:49152
	ds_read_b128 v[8:11], v14 offset:57344
	v_xor_b32_e32 v14, 0x80, v14
	s_waitcnt vmcnt(1) lgkmcnt(1)
	v_mfma_f32_32x32x16_bf16 v[82:97], v[4:7], v[150:153], v[82:97]
	s_waitcnt lgkmcnt(0)
	v_mfma_f32_32x32x16_bf16 v[98:113], v[8:11], v[150:153], v[98:113]
	v_xor_b32_e32 v3, 0x80, v3
	ds_read_b128 v[4:7], v3 offset:49152
	ds_read_b128 v[8:11], v3 offset:57344
	v_xor_b32_e32 v3, 0x80, v3
	s_waitcnt vmcnt(0) lgkmcnt(1)
	v_mfma_f32_32x32x16_bf16 v[82:97], v[4:7], v[146:149], v[82:97]
	s_waitcnt lgkmcnt(0)
	v_mfma_f32_32x32x16_bf16 v[98:113], v[8:11], v[146:149], v[98:113]
	s_branch .LBB0_864
